# prep token loop rewritten by hand: wave=token row, lane=4 channels, dwordx2 loads/stores, row-16 DPP sums, loads 3 tokens ahead
# speedup vs baseline: 1.0658x; 1.0103x over previous
.LBB0_334:
	s_mov_b32 s4, 0xf149f2ca
	v_max3_f32 v32, v147, s4, v146
	v_max3_f32 v32, v32, v119, v145
	v_max3_f32 v32, v32, v51, v52
	v_max3_f32 v32, v32, v48, v50
	v_max3_f32 v32, v32, v49, v53
	v_max3_f32 v32, v32, v54, v55
	v_max3_f32 v32, v32, v56, v57
	v_max3_f32 v32, v32, v58, v59
	v_max3_f32 v32, v32, v60, v61
	v_max3_f32 v32, v32, v62, v150
	v_max3_f32 v32, v32, v151, v153
	v_max3_f32 v32, v32, v149, v152
	v_max3_f32 v32, v32, v63, v148
	v_max3_f32 v32, v32, v41, v42
	v_max3_f32 v32, v32, v39, v45
	v_max3_f32 v32, v32, v46, v154
	ds_bpermute_b32 v33, v121, v32
	v_cmp_lt_f32_e32 vcc, s86, v147
	s_add_i32 s44, s44, 1
	s_movk_i32 s96, 0x101
	v_add_u32_e32 v118, 64, v118
	s_waitcnt lgkmcnt(0)
	v_max3_f32 v33, v144, v32, v33
	v_sub_f32_e32 v34, v147, v33
	v_mul_f32_e32 v34, 0x3fb8aa3b, v34
	v_sub_f32_e32 v36, v146, v33
	v_exp_f32_e32 v34, v34
	v_mul_f32_e32 v36, 0x3fb8aa3b, v36
	v_exp_f32_e32 v36, v36
	v_sub_f32_e32 v32, v144, v33
	v_cndmask_b32_e32 v35, 0, v34, vcc
	v_cmp_lt_f32_e32 vcc, s86, v146
	v_add_f32_e32 v34, 0, v35
	v_mul_f32_e32 v32, 0x3fb8aa3b, v32
	v_cndmask_b32_e32 v38, 0, v36, vcc
	v_sub_f32_e32 v36, v119, v33
	v_mul_f32_e32 v36, 0x3fb8aa3b, v36
	v_exp_f32_e32 v36, v36
	v_cmp_lt_f32_e32 vcc, s86, v119
	v_add_f32_e32 v34, v38, v34
	v_exp_f32_e32 v32, v32
	v_cndmask_b32_e32 v43, 0, v36, vcc
	v_sub_f32_e32 v36, v145, v33
	v_mul_f32_e32 v36, 0x3fb8aa3b, v36
	v_exp_f32_e32 v36, v36
	v_cmp_lt_f32_e32 vcc, s86, v145
	v_add_f32_e32 v34, v43, v34
	v_cvt_pk_bf16_f32 v146, v35, v38
	v_cndmask_b32_e32 v47, 0, v36, vcc
	v_sub_f32_e32 v36, v51, v33
	v_mul_f32_e32 v36, 0x3fb8aa3b, v36
	v_exp_f32_e32 v36, v36
	v_cmp_lt_f32_e32 vcc, s86, v51
	v_add_f32_e32 v34, v47, v34
	v_add_u32_e32 v38, 0x2000, v142
	v_cndmask_b32_e32 v51, 0, v36, vcc
	v_sub_f32_e32 v36, v52, v33
	v_mul_f32_e32 v36, 0x3fb8aa3b, v36
	v_exp_f32_e32 v36, v36
	v_cmp_lt_f32_e32 vcc, s86, v52
	v_add_f32_e32 v34, v51, v34
	v_pk_mul_f32 v[30:31], v[30:31], v[32:33] op_sel_hi:[1,0]
	v_cndmask_b32_e32 v52, 0, v36, vcc
	v_sub_f32_e32 v36, v48, v33
	v_mul_f32_e32 v36, 0x3fb8aa3b, v36
	v_exp_f32_e32 v36, v36
	v_cmp_lt_f32_e32 vcc, s86, v48
	v_add_f32_e32 v34, v52, v34
	v_pk_mul_f32 v[28:29], v[28:29], v[32:33] op_sel_hi:[1,0]
	v_cndmask_b32_e32 v119, 0, v36, vcc
	v_sub_f32_e32 v36, v50, v33
	v_mul_f32_e32 v36, 0x3fb8aa3b, v36
	v_exp_f32_e32 v36, v36
	v_cmp_lt_f32_e32 vcc, s86, v50
	v_add_f32_e32 v34, v119, v34
	v_pk_mul_f32 v[26:27], v[26:27], v[32:33] op_sel_hi:[1,0]
	v_cndmask_b32_e32 v144, 0, v36, vcc
	v_add_f32_e32 v36, v144, v34
	v_sub_f32_e32 v34, v49, v33
	v_mul_f32_e32 v34, 0x3fb8aa3b, v34
	v_exp_f32_e32 v34, v34
	v_cmp_lt_f32_e32 vcc, s86, v49
	v_pk_mul_f32 v[24:25], v[24:25], v[32:33] op_sel_hi:[1,0]
	v_pk_mul_f32 v[22:23], v[22:23], v[32:33] op_sel_hi:[1,0]
	v_cndmask_b32_e32 v34, 0, v34, vcc
	v_add_f32_e32 v37, v34, v36
	v_sub_f32_e32 v36, v53, v33
	v_mul_f32_e32 v36, 0x3fb8aa3b, v36
	v_exp_f32_e32 v36, v36
	v_cmp_lt_f32_e32 vcc, s86, v53
	v_sub_f32_e32 v53, v59, v33
	v_mul_f32_e32 v53, 0x3fb8aa3b, v53
	v_cndmask_b32_e32 v36, 0, v36, vcc
	v_add_f32_e32 v40, v36, v37
	v_sub_f32_e32 v37, v54, v33
	v_mul_f32_e32 v37, 0x3fb8aa3b, v37
	v_exp_f32_e32 v37, v37
	v_cmp_lt_f32_e32 vcc, s86, v54
	v_exp_f32_e32 v53, v53
	v_pk_mul_f32 v[20:21], v[20:21], v[32:33] op_sel_hi:[1,0]
	v_cndmask_b32_e32 v37, 0, v37, vcc
	v_add_f32_e32 v44, v37, v40
	v_sub_f32_e32 v40, v55, v33
	v_mul_f32_e32 v40, 0x3fb8aa3b, v40
	v_exp_f32_e32 v40, v40
	v_cmp_lt_f32_e32 vcc, s86, v55
	v_pk_mul_f32 v[18:19], v[18:19], v[32:33] op_sel_hi:[1,0]
	v_pk_mul_f32 v[16:17], v[16:17], v[32:33] op_sel_hi:[1,0]
	v_cndmask_b32_e32 v40, 0, v40, vcc
	v_add_f32_e32 v48, v40, v44
	v_sub_f32_e32 v44, v56, v33
	v_mul_f32_e32 v44, 0x3fb8aa3b, v44
	v_exp_f32_e32 v44, v44
	v_cmp_lt_f32_e32 vcc, s86, v56
	v_cvt_pk_bf16_f32 v147, v43, v47
	v_add_u32_e32 v47, 0x3000, v142
	v_cndmask_b32_e32 v44, 0, v44, vcc
	v_add_f32_e32 v49, v44, v48
	v_sub_f32_e32 v48, v57, v33
	v_mul_f32_e32 v48, 0x3fb8aa3b, v48
	v_exp_f32_e32 v48, v48
	v_cmp_lt_f32_e32 vcc, s86, v57
	v_sub_f32_e32 v57, v150, v33
	v_mul_f32_e32 v57, 0x3fb8aa3b, v57
	v_cndmask_b32_e32 v48, 0, v48, vcc
	v_add_f32_e32 v50, v48, v49
	v_sub_f32_e32 v49, v58, v33
	v_mul_f32_e32 v49, 0x3fb8aa3b, v49
	v_exp_f32_e32 v49, v49
	v_cmp_lt_f32_e32 vcc, s86, v58
	v_sub_f32_e32 v58, v151, v33
	v_exp_f32_e32 v57, v57
	v_cndmask_b32_e32 v49, 0, v49, vcc
	v_cmp_lt_f32_e32 vcc, s86, v59
	v_add_f32_e32 v50, v49, v50
	v_mul_f32_e32 v58, 0x3fb8aa3b, v58
	v_cndmask_b32_e32 v53, 0, v53, vcc
	v_add_f32_e32 v54, v53, v50
	v_sub_f32_e32 v50, v60, v33
	v_mul_f32_e32 v50, 0x3fb8aa3b, v50
	v_exp_f32_e32 v50, v50
	v_cmp_lt_f32_e32 vcc, s86, v60
	v_sub_f32_e32 v59, v153, v33
	v_exp_f32_e32 v58, v58
	v_cndmask_b32_e32 v50, 0, v50, vcc
	v_add_f32_e32 v55, v50, v54
	v_sub_f32_e32 v54, v61, v33
	v_mul_f32_e32 v54, 0x3fb8aa3b, v54
	v_exp_f32_e32 v54, v54
	v_cmp_lt_f32_e32 vcc, s86, v61
	v_mul_f32_e32 v59, 0x3fb8aa3b, v59
	v_exp_f32_e32 v59, v59
	v_cndmask_b32_e32 v54, 0, v54, vcc
	v_add_f32_e32 v56, v54, v55
	v_sub_f32_e32 v55, v62, v33
	v_mul_f32_e32 v55, 0x3fb8aa3b, v55
	v_exp_f32_e32 v55, v55
	v_cmp_lt_f32_e32 vcc, s86, v62
	v_pk_mul_f32 v[14:15], v[14:15], v[32:33] op_sel_hi:[1,0]
	v_pk_mul_f32 v[12:13], v[12:13], v[32:33] op_sel_hi:[1,0]
	v_cndmask_b32_e32 v55, 0, v55, vcc
	v_cmp_lt_f32_e32 vcc, s86, v150
	v_add_f32_e32 v56, v55, v56
	v_pk_mul_f32 v[10:11], v[10:11], v[32:33] op_sel_hi:[1,0]
	v_cndmask_b32_e32 v57, 0, v57, vcc
	v_cmp_lt_f32_e32 vcc, s86, v151
	v_add_f32_e32 v56, v57, v56
	v_pk_mul_f32 v[8:9], v[8:9], v[32:33] op_sel_hi:[1,0]
	v_cndmask_b32_e32 v58, 0, v58, vcc
	v_cmp_lt_f32_e32 vcc, s86, v153
	v_add_f32_e32 v56, v58, v56
	v_pk_mul_f32 v[6:7], v[6:7], v[32:33] op_sel_hi:[1,0]
	v_cndmask_b32_e32 v60, 0, v59, vcc
	v_sub_f32_e32 v59, v149, v33
	v_mul_f32_e32 v59, 0x3fb8aa3b, v59
	v_exp_f32_e32 v59, v59
	v_cmp_lt_f32_e32 vcc, s86, v149
	v_add_f32_e32 v56, v60, v56
	v_cvt_pk_bf16_f32 v149, v119, v144
	v_cndmask_b32_e32 v61, 0, v59, vcc
	v_sub_f32_e32 v59, v152, v33
	v_mul_f32_e32 v59, 0x3fb8aa3b, v59
	v_exp_f32_e32 v59, v59
	v_cmp_lt_f32_e32 vcc, s86, v152
	v_add_f32_e32 v56, v61, v56
	v_pk_mul_f32 v[4:5], v[4:5], v[32:33] op_sel_hi:[1,0]
	v_cndmask_b32_e32 v62, 0, v59, vcc
	v_add_f32_e32 v59, v62, v56
	v_sub_f32_e32 v56, v63, v33
	v_mul_f32_e32 v56, 0x3fb8aa3b, v56
	v_exp_f32_e32 v56, v56
	v_cmp_lt_f32_e32 vcc, s86, v63
	v_pk_mul_f32 v[2:3], v[2:3], v[32:33] op_sel_hi:[1,0]
	v_pk_mul_f32 v[0:1], v[0:1], v[32:33] op_sel_hi:[1,0]
	v_cndmask_b32_e32 v56, 0, v56, vcc
	v_add_f32_e32 v63, v56, v59
	v_sub_f32_e32 v59, v148, v33
	v_mul_f32_e32 v59, 0x3fb8aa3b, v59
	v_exp_f32_e32 v59, v59
	v_cmp_lt_f32_e32 vcc, s86, v148
	v_cvt_pk_bf16_f32 v148, v51, v52
	v_cvt_pk_bf16_f32 v34, v34, v36
	v_cndmask_b32_e32 v59, 0, v59, vcc
	v_cmp_lt_f32_e32 vcc, s86, v41
	v_sub_f32_e32 v41, v41, v33
	v_mul_f32_e32 v41, 0x3fb8aa3b, v41
	v_exp_f32_e32 v41, v41
	v_add_f32_e32 v63, v59, v63
	v_cvt_pk_bf16_f32 v36, v44, v48
	v_cvt_pk_bf16_f32 v35, v37, v40
	v_cndmask_b32_e32 v41, 0, v41, vcc
	v_cmp_lt_f32_e32 vcc, s86, v42
	v_sub_f32_e32 v42, v42, v33
	v_mul_f32_e32 v42, 0x3fb8aa3b, v42
	v_exp_f32_e32 v42, v42
	v_add_f32_e32 v63, v41, v63
	v_cvt_pk_bf16_f32 v37, v49, v53
	v_add_u32_e32 v124, 31, v124
	v_cndmask_b32_e32 v134, 0, v42, vcc
	v_cmp_lt_f32_e32 vcc, s86, v39
	v_sub_f32_e32 v39, v39, v33
	v_mul_f32_e32 v39, 0x3fb8aa3b, v39
	v_exp_f32_e32 v39, v39
	v_add_f32_e32 v42, v134, v63
	v_add_u32_e32 v125, 64, v125
	s_cmp_lg_u32 s46, s44
	v_cndmask_b32_e32 v63, 0, v39, vcc
	v_add_f32_e32 v39, v63, v42
	v_sub_f32_e32 v42, v45, v33
	v_mul_f32_e32 v42, 0x3fb8aa3b, v42
	v_exp_f32_e32 v42, v42
	v_cmp_lt_f32_e32 vcc, s86, v45
	s_nop 1
	v_cndmask_b32_e32 v135, 0, v42, vcc
	v_sub_f32_e32 v42, v46, v33
	v_mul_f32_e32 v42, 0x3fb8aa3b, v42
	v_exp_f32_e32 v42, v42
	v_cmp_lt_f32_e32 vcc, s86, v46
	v_add_f32_e32 v39, v135, v39
	s_nop 0
	v_cndmask_b32_e32 v46, 0, v42, vcc
	v_sub_f32_e32 v42, v154, v33
	v_cmp_lt_f32_e32 vcc, s86, v154
	v_mul_f32_e32 v42, 0x3fb8aa3b, v42
	ds_read2_b64 v[150:153], v38 offset1:2
	ds_read2_b64 v[154:157], v38 offset0:4 offset1:6
	v_exp_f32_e32 v42, v42
	s_waitcnt lgkmcnt(1)
	v_mfma_f32_32x32x16_bf16 v[16:31], v[150:153], v[146:149], v[16:31]
	ds_read2_b64 v[150:153], v47 offset0:32 offset1:34
	v_add_f32_e32 v39, v46, v39
	v_cndmask_b32_e32 v136, 0, v42, vcc
	v_add_f32_e32 v39, v136, v39
	ds_bpermute_b32 v42, v121, v39
	s_waitcnt lgkmcnt(0)
	v_add_f32_e32 v39, v39, v42
	ds_read2_b64 v[42:45], v47 offset0:36 offset1:38
	v_mfma_f32_32x32x16_bf16 v[0:15], v[150:153], v[146:149], v[0:15]
	v_fmac_f32_e32 v39, v143, v32
	s_waitcnt lgkmcnt(0)
	v_mfma_f32_32x32x16_bf16 v[0:15], v[42:45], v[34:37], v[0:15]
	ds_read2_b64 v[42:45], v38 offset0:8 offset1:10
	v_mfma_f32_32x32x16_bf16 v[16:31], v[154:157], v[34:37], v[16:31]
	v_cvt_pk_bf16_f32 v34, v50, v54
	v_cvt_pk_bf16_f32 v35, v55, v57
	v_cvt_pk_bf16_f32 v36, v58, v60
	v_cvt_pk_bf16_f32 v37, v61, v62
	s_waitcnt lgkmcnt(0)
	s_nop 0
	v_mfma_f32_32x32x16_bf16 v[16:31], v[42:45], v[34:37], v[16:31]
	ds_read2_b64 v[42:45], v47 offset0:40 offset1:42
	s_waitcnt lgkmcnt(0)
	v_mfma_f32_32x32x16_bf16 v[0:15], v[42:45], v[34:37], v[0:15]
	v_cvt_pk_bf16_f32 v35, v41, v134
	ds_read2_b64 v[40:43], v38 offset0:12 offset1:14
	v_cvt_pk_bf16_f32 v34, v56, v59
	v_cvt_pk_bf16_f32 v36, v63, v135
	v_cvt_pk_bf16_f32 v37, v46, v136
	s_waitcnt lgkmcnt(0)
	s_nop 0
	v_mfma_f32_32x32x16_bf16 v[16:31], v[40:43], v[34:37], v[16:31]
	ds_read2_b64 v[40:43], v47 offset0:44 offset1:46
	s_waitcnt lgkmcnt(0)
	v_mfma_f32_32x32x16_bf16 v[0:15], v[40:43], v[34:37], v[0:15]
	s_cbranch_scc0 .LBB0_336
	v_mov_b32_e32 v144, v33
	v_mov_b32_e32 v143, v39
	s_branch .LBB0_262
.Ltramp_678:
	s_branch .LBB0_678
.LBB0_336:
	v_div_scale_f32 v32, s[0:1], v39, v39, 1.0
	v_rcp_f32_e32 v33, v32
	v_div_scale_f32 v34, vcc, 1.0, v39, 1.0
	v_readlane_b32 s0, v254, 43
	v_fma_f32 v35, -v32, v33, 1.0
	v_fmac_f32_e32 v33, v35, v33
	v_mul_f32_e32 v35, v34, v33
	v_fma_f32 v36, -v32, v35, v34
	v_fmac_f32_e32 v35, v36, v33
	v_fma_f32 v32, -v32, v35, v34
	v_div_fmas_f32 v32, v32, v33, v35
	v_lshlrev_b64 v[34:35], 11, v[112:113]
	v_readlane_b32 s1, v254, 44
	v_div_fixup_f32 v32, v32, v39, 1.0
	s_lshl_b32 s92, s83, 1
	v_lshl_add_u64 v[34:35], s[0:1], 0, v[34:35]
	v_lshl_add_u64 v[34:35], v[34:35], 0, s[92:93]
	v_pk_mul_f32 v[16:17], v[16:17], v[32:33] op_sel_hi:[1,0]
	v_pk_mul_f32 v[18:19], v[18:19], v[32:33] op_sel_hi:[1,0]
	v_lshlrev_b32_e32 v128, 1, v114
	v_cvt_pk_bf16_f32 v16, v16, v17
	v_cvt_pk_bf16_f32 v17, v18, v19
	v_lshl_add_u64 v[18:19], v[34:35], 0, v[128:129]
	s_mov_b64 s[0:1], 0x153ca200
	v_lshl_add_u64 v[34:35], v[18:19], 0, s[0:1]
	s_mov_b32 s0, 0x153ca000
	v_add_co_u32_e32 v18, vcc, s0, v18
	v_pk_mul_f32 v[0:1], v[32:33], v[0:1] op_sel_hi:[0,1]
	v_pk_mul_f32 v[2:3], v[32:33], v[2:3] op_sel_hi:[0,1]
	v_addc_co_u32_e32 v19, vcc, 0, v19, vcc
	v_cvt_pk_bf16_f32 v0, v0, v1
	v_cvt_pk_bf16_f32 v1, v2, v3
	global_store_dwordx2 v[18:19], v[16:17], off offset:512
	v_pk_mul_f32 v[16:17], v[20:21], v[32:33] op_sel_hi:[1,0]
	v_pk_mul_f32 v[18:19], v[22:23], v[32:33] op_sel_hi:[1,0]
	global_store_dwordx2 v[34:35], v[0:1], off offset:64
	v_pk_mul_f32 v[0:1], v[32:33], v[4:5] op_sel_hi:[0,1]
	v_pk_mul_f32 v[2:3], v[32:33], v[6:7] op_sel_hi:[0,1]
	v_cvt_pk_bf16_f32 v16, v16, v17
	v_cvt_pk_bf16_f32 v17, v18, v19
	v_cvt_pk_bf16_f32 v0, v0, v1
	v_cvt_pk_bf16_f32 v1, v2, v3
	global_store_dwordx2 v[34:35], v[16:17], off offset:16
	v_pk_mul_f32 v[16:17], v[24:25], v[32:33] op_sel_hi:[1,0]
	v_pk_mul_f32 v[18:19], v[26:27], v[32:33] op_sel_hi:[1,0]
	global_store_dwordx2 v[34:35], v[0:1], off offset:80
	v_pk_mul_f32 v[0:1], v[32:33], v[8:9] op_sel_hi:[0,1]
	v_pk_mul_f32 v[2:3], v[32:33], v[10:11] op_sel_hi:[0,1]
	v_cvt_pk_bf16_f32 v16, v16, v17
	v_cvt_pk_bf16_f32 v17, v18, v19
	v_cvt_pk_bf16_f32 v0, v0, v1
	v_cvt_pk_bf16_f32 v1, v2, v3
	global_store_dwordx2 v[34:35], v[16:17], off offset:32
	v_pk_mul_f32 v[16:17], v[28:29], v[32:33] op_sel_hi:[1,0]
	v_pk_mul_f32 v[18:19], v[30:31], v[32:33] op_sel_hi:[1,0]
	global_store_dwordx2 v[34:35], v[0:1], off offset:96
	v_pk_mul_f32 v[0:1], v[32:33], v[12:13] op_sel_hi:[0,1]
	v_pk_mul_f32 v[2:3], v[32:33], v[14:15] op_sel_hi:[0,1]
	v_cvt_pk_bf16_f32 v16, v16, v17
	v_cvt_pk_bf16_f32 v17, v18, v19
	v_cvt_pk_bf16_f32 v0, v0, v1
	v_cvt_pk_bf16_f32 v1, v2, v3
	global_store_dwordx2 v[34:35], v[16:17], off offset:48
	global_store_dwordx2 v[34:35], v[0:1], off offset:112
	s_barrier

.LBB0_485:
	s_or_b64 exec, exec, s[6:7]
	v_lshl_add_u32 v0, s0, 8, v32
	v_readlane_b32 s60, v253, 46
	v_ashrrev_i32_e32 v1, 31, v0
	v_readlane_b32 s61, v253, 47
	v_readlane_b32 s62, v253, 48
	v_readlane_b32 s63, v253, 49
	v_readlane_b32 s64, v253, 50
	v_readlane_b32 s65, v253, 51
	v_readlane_b32 s66, v253, 52
	v_readlane_b32 s67, v253, 53
	v_lshlrev_b64 v[2:3], 2, v[0:1]
	v_readlane_b32 s52, v253, 62
	v_lshl_add_u32 v0, s0, 9, v0
	v_readlane_b32 s70, v253, 56
	v_readlane_b32 s71, v253, 57
	v_readlane_b32 s74, v253, 60
	v_readlane_b32 s75, v253, 61
	v_readlane_b32 s54, v254, 0
	v_readlane_b32 s55, v254, 1
	v_ashrrev_i32_e32 v1, 31, v0
	v_lshl_add_u64 v[4:5], s[74:75], 0, v[2:3]
	v_lshl_add_u64 v[2:3], s[54:55], 0, v[2:3]
	s_mul_i32 s1, s0, 0x300
	v_lshl_add_u64 v[0:1], v[0:1], 2, s[70:71]
	s_waitcnt lgkmcnt(0)
	s_barrier
	s_xor_b64 s[18:19], s[16:17], -1
	v_readlane_b32 s22, v254, 34
	v_readlane_b32 s56, v254, 30
	v_readlane_b32 s57, v254, 31
	s_sub_u32 s56, s56, 0x110
	s_subb_u32 s57, s57, 0
	s_load_dwordx2 s[58:59], s[56:57], 0x68
	s_load_dwordx2 s[60:61], s[56:57], 0x78
	s_load_dwordx2 s[62:63], s[56:57], 0x88
	s_load_dwordx4 s[64:67], s[56:57], 0xa0
	s_load_dwordx2 s[68:69], s[56:57], 0xb0
	v_readlane_b32 s72, v254, 43
	v_readlane_b32 s73, v254, 44
	v_readlane_b32 s92, v254, 49
	v_readfirstlane_b32 s0, v160
	s_lshr_b32 s0, s0, 6
	s_and_b32 s0, s0, 3
	s_mul_i32 s53, s51, 20
	s_add_i32 s53, s53, s0
	s_lshl_b32 s0, s0, 10
	s_add_i32 s92, s92, s0
	v_and_b32_e32 v250, 63, v160
	v_lshlrev_b32_e32 v251, 4, v250
	v_lshlrev_b32_e32 v250, 3, v250
	v_add_u32_e32 v31, s92, v251
	s_add_u32 s28, s72, 0x664a000
	s_addc_u32 s29, s73, 0
	s_add_u32 s34, s72, 0xaeca000
	s_addc_u32 s35, s73, 0
	s_add_u32 s42, s72, 0x13aca000
	s_addc_u32 s43, s73, 0
	s_waitcnt lgkmcnt(0)
	s_cmp_eq_u64 s[16:17], 0
	s_cbranch_scc1 .Lprep_tok_d1
	s_mul_i32 s0, s22, 2
	s_add_i32 s0, s0, 0
	s_lshl_b32 s1, s0, 10
	s_add_u32 s60, s60, s1
	s_addc_u32 s61, s61, 0
	s_add_u32 s62, s62, s1
	s_addc_u32 s63, s63, 0
	s_mul_i32 s1, s0, 0xc00
	s_add_u32 s58, s58, s1
	s_addc_u32 s59, s59, 0
	s_lshl_b32 s1, s22, 10
	s_add_u32 s64, s64, s1
	s_addc_u32 s65, s65, 0
	s_add_u32 s66, s66, s1
	s_addc_u32 s67, s67, 0
	s_add_u32 s68, s68, s1
	s_addc_u32 s69, s69, 0
	global_load_dwordx4 v[210:213], v251, s[58:59] offset:0
	global_load_dwordx4 v[214:217], v251, s[58:59] offset:1024
	global_load_dwordx4 v[218:221], v251, s[58:59] offset:2048
	global_load_dwordx4 v[198:201], v251, s[64:65] offset:0
	global_load_dwordx4 v[194:197], v251, s[62:63] offset:0
	global_load_dwordx4 v[190:193], v251, s[60:61] offset:0
	global_load_dwordx4 v[202:205], v251, s[66:67] offset:0
	global_load_dwordx4 v[206:209], v251, s[68:69] offset:0
	s_add_i32 s56, s53, 0
	s_cmpk_lt_i32 s56, 0x2000
	s_movk_i32 s0, 0x3ff
	s_cselect_b32 s0, 0xff, s0
	s_and_b32 s1, s56, s0
	s_cmp_lg_u32 s1, 0
	s_cselect_b32 s59, 1.0, 0
	s_cselect_b32 s1, -1, 0
	s_add_i32 s1, s56, s1
	s_mul_i32 s0, s56, 0x1d00
	s_add_u32 s76, s28, s0
	s_addc_u32 s77, s29, 0
	s_mul_i32 s0, s1, 0x1d00
	s_add_u32 s78, s28, s0
	s_addc_u32 s79, s29, 0
	global_load_dwordx2 v[222:223], v250, s[76:77] offset:0
	global_load_dwordx2 v[224:225], v250, s[76:77] offset:512
	global_load_dwordx2 v[226:227], v250, s[76:77] offset:1024
	global_load_dwordx2 v[228:229], v250, s[78:79] offset:0
	global_load_dwordx2 v[230:231], v250, s[78:79] offset:512
	global_load_dwordx2 v[232:233], v250, s[78:79] offset:1024
	s_add_i32 s57, s53, 4
	s_cmpk_lt_i32 s57, 0x2000
	s_movk_i32 s0, 0x3ff
	s_cselect_b32 s0, 0xff, s0
	s_and_b32 s1, s57, s0
	s_cmp_lg_u32 s1, 0
	s_cselect_b32 s60, 1.0, 0
	s_cselect_b32 s1, -1, 0
	s_add_i32 s1, s57, s1
	s_mul_i32 s0, s57, 0x1d00
	s_add_u32 s80, s28, s0
	s_addc_u32 s81, s29, 0
	s_mul_i32 s0, s1, 0x1d00
	s_add_u32 s82, s28, s0
	s_addc_u32 s83, s29, 0
	global_load_dwordx2 v[236:237], v250, s[80:81] offset:0
	global_load_dwordx2 v[238:239], v250, s[80:81] offset:512
	global_load_dwordx2 v[240:241], v250, s[80:81] offset:1024
	global_load_dwordx2 v[242:243], v250, s[82:83] offset:0
	global_load_dwordx2 v[244:245], v250, s[82:83] offset:512
	global_load_dwordx2 v[246:247], v250, s[82:83] offset:1024
	s_add_i32 s58, s53, 8
	s_cmpk_lt_i32 s58, 0x2000
	s_movk_i32 s0, 0x3ff
	s_cselect_b32 s0, 0xff, s0
	s_and_b32 s1, s58, s0
	s_cmp_lg_u32 s1, 0
	s_cselect_b32 s61, 1.0, 0
	s_cselect_b32 s1, -1, 0
	s_add_i32 s1, s58, s1
	s_mul_i32 s0, s58, 0x1d00
	s_add_u32 s84, s28, s0
	s_addc_u32 s85, s29, 0
	s_mul_i32 s0, s1, 0x1d00
	s_add_u32 s96, s28, s0
	s_addc_u32 s97, s29, 0
	global_load_dwordx2 v[0:1], v250, s[84:85] offset:0
	global_load_dwordx2 v[2:3], v250, s[84:85] offset:512
	global_load_dwordx2 v[4:5], v250, s[84:85] offset:1024
	global_load_dwordx2 v[6:7], v250, s[96:97] offset:0
	global_load_dwordx2 v[8:9], v250, s[96:97] offset:512
	global_load_dwordx2 v[10:11], v250, s[96:97] offset:1024
	ds_read_b128 v[14:17], v31 offset:0
	ds_read_b128 v[18:21], v31 offset:20480
	ds_read_b128 v[22:25], v31 offset:4096
	ds_read_b128 v[26:29], v31 offset:24576
	s_waitcnt vmcnt(18)
	s_waitcnt vmcnt(12)
	v_lshlrev_b32_e32 v134, 16, v222
	v_and_b32_e32 v222, 0xffff0000, v222
	v_lshlrev_b32_e32 v135, 16, v223
	v_and_b32_e32 v223, 0xffff0000, v223
	v_lshlrev_b32_e32 v136, 16, v224
	v_and_b32_e32 v224, 0xffff0000, v224
	v_lshlrev_b32_e32 v137, 16, v225
	v_and_b32_e32 v225, 0xffff0000, v225
	v_lshlrev_b32_e32 v138, 16, v226
	v_and_b32_e32 v226, 0xffff0000, v226
	v_lshlrev_b32_e32 v139, 16, v227
	v_and_b32_e32 v227, 0xffff0000, v227
	v_lshlrev_b32_e32 v140, 16, v228
	v_and_b32_e32 v228, 0xffff0000, v228
	v_lshlrev_b32_e32 v141, 16, v229
	v_and_b32_e32 v229, 0xffff0000, v229
	v_lshlrev_b32_e32 v142, 16, v230
	v_and_b32_e32 v230, 0xffff0000, v230
	v_lshlrev_b32_e32 v143, 16, v231
	v_and_b32_e32 v231, 0xffff0000, v231
	v_lshlrev_b32_e32 v144, 16, v232
	v_and_b32_e32 v232, 0xffff0000, v232
	v_lshlrev_b32_e32 v145, 16, v233
	v_and_b32_e32 v233, 0xffff0000, v233
	v_fma_f32 v140, s59, v140, -v134
	v_fma_f32 v228, s59, v228, -v222
	v_fma_f32 v141, s59, v141, -v135
	v_fma_f32 v229, s59, v229, -v223
	v_fmac_f32_e32 v134, v210, v140
	v_fmac_f32_e32 v222, v211, v228
	v_fmac_f32_e32 v135, v212, v141
	v_fmac_f32_e32 v223, v213, v229
	v_fma_f32 v142, s59, v142, -v136
	v_fma_f32 v230, s59, v230, -v224
	v_fma_f32 v143, s59, v143, -v137
	v_fma_f32 v231, s59, v231, -v225
	v_fmac_f32_e32 v136, v214, v142
	v_fmac_f32_e32 v224, v215, v230
	v_fmac_f32_e32 v137, v216, v143
	v_fmac_f32_e32 v225, v217, v231
	v_fma_f32 v144, s59, v144, -v138
	v_fma_f32 v232, s59, v232, -v226
	v_fma_f32 v145, s59, v145, -v139
	v_fma_f32 v233, s59, v233, -v227
	v_fmac_f32_e32 v138, v218, v144
	v_fmac_f32_e32 v226, v219, v232
	v_fmac_f32_e32 v139, v220, v145
	v_fmac_f32_e32 v227, v221, v233
	v_mul_f32_e32 v148, v198, v136
	v_mul_f32_e32 v149, v199, v224
	v_mul_f32_e32 v150, v200, v137
	v_mul_f32_e32 v151, v201, v225
	v_mul_f32_e32 v176, v148, v148
	v_fmac_f32_e32 v176, v149, v149
	v_fmac_f32_e32 v176, v150, v150
	v_fmac_f32_e32 v176, v151, v151
	s_waitcnt lgkmcnt(2)
	v_add_f32_e32 v18, v194, v18
	v_add_f32_e32 v19, v195, v19
	v_add_f32_e32 v20, v196, v20
	v_add_f32_e32 v21, v197, v21
	v_add_f32_dpp v176, v176, v176 quad_perm:[1,0,3,2] row_mask:0xf bank_mask:0xf bound_ctrl:1
	v_mul_f32_e32 v18, 0xbfb8aa3b, v18
	v_mul_f32_e32 v19, 0xbfb8aa3b, v19
	v_mul_f32_e32 v20, 0xbfb8aa3b, v20
	v_mul_f32_e32 v21, 0xbfb8aa3b, v21
	v_add_f32_dpp v176, v176, v176 quad_perm:[2,3,0,1] row_mask:0xf bank_mask:0xf bound_ctrl:1
	v_exp_f32_e32 v18, v18
	v_exp_f32_e32 v19, v19
	v_exp_f32_e32 v20, v20
	v_exp_f32_e32 v21, v21
	v_add_f32_dpp v176, v176, v176 row_half_mirror row_mask:0xf bank_mask:0xf bound_ctrl:1
	v_add_f32_e32 v18, 1.0, v18
	v_add_f32_e32 v19, 1.0, v19
	v_add_f32_e32 v20, 1.0, v20
	v_add_f32_e32 v21, 1.0, v21
	v_add_f32_dpp v176, v176, v176 row_mirror row_mask:0xf bank_mask:0xf bound_ctrl:1
	v_rcp_f32_e32 v18, v18
	v_rcp_f32_e32 v19, v19
	v_rcp_f32_e32 v20, v20
	v_rcp_f32_e32 v21, v21
	v_sqrt_f32_e32 v176, v176
	v_add_f32_e32 v14, v190, v14
	v_add_f32_e32 v15, v191, v15
	v_add_f32_e32 v16, v192, v16
	v_add_f32_e32 v17, v193, v17
	v_max_f32_e32 v176, 0x2b8cbccc, v176
	v_mul_f32_e32 v14, 0xbfb8aa3b, v14
	v_mul_f32_e32 v15, 0xbfb8aa3b, v15
	v_mul_f32_e32 v16, 0xbfb8aa3b, v16
	v_mul_f32_e32 v17, 0xbfb8aa3b, v17
	v_rcp_f32_e32 v178, v176
	v_exp_f32_e32 v14, v14
	v_exp_f32_e32 v15, v15
	v_exp_f32_e32 v16, v16
	v_exp_f32_e32 v17, v17
	v_add_f32_e32 v14, 1.0, v14
	v_add_f32_e32 v15, 1.0, v15
	v_add_f32_e32 v16, 1.0, v16
	v_add_f32_e32 v17, 1.0, v17
	v_rcp_f32_e32 v14, v14
	v_rcp_f32_e32 v15, v15
	v_rcp_f32_e32 v16, v16
	v_rcp_f32_e32 v17, v17
	v_mul_f32_e32 v14, 0xbf1b4598, v14
	v_mul_f32_e32 v15, 0xbf1b4598, v15
	v_mul_f32_e32 v16, 0xbf1b4598, v16
	v_mul_f32_e32 v17, 0xbf1b4598, v17
	v_mul_f32_e32 v14, 0x3fb8aa3b, v14
	v_mul_f32_e32 v15, 0x3fb8aa3b, v15
	v_mul_f32_e32 v16, 0x3fb8aa3b, v16
	v_mul_f32_e32 v17, 0x3fb8aa3b, v17
	v_exp_f32_e32 v14, v14
	v_exp_f32_e32 v15, v15
	v_exp_f32_e32 v16, v16
	v_exp_f32_e32 v17, v17
	v_add_f32_e32 v152, -1.0, v18
	v_add_f32_e32 v153, -1.0, v19
	v_add_f32_e32 v154, -1.0, v20
	v_add_f32_e32 v155, -1.0, v21
	v_fma_f32 v152, v202, v152, 1.0
	v_fma_f32 v153, v203, v153, 1.0
	v_fma_f32 v154, v204, v154, 1.0
	v_fma_f32 v155, v205, v155, 1.0
	v_mul_f32_e32 v152, v136, v152
	v_mul_f32_e32 v153, v224, v153
	v_mul_f32_e32 v154, v137, v154
	v_mul_f32_e32 v155, v225, v155
	v_mul_f32_e32 v156, v134, v152
	v_mul_f32_e32 v157, v222, v153
	v_mul_f32_e32 v158, v135, v154
	v_mul_f32_e32 v159, v223, v155
	v_mul_f32_e32 v177, v206, v156
	v_fmac_f32_e32 v177, v207, v157
	v_fmac_f32_e32 v177, v208, v158
	v_fmac_f32_e32 v177, v209, v159
	v_mul_f32_e32 v148, v148, v178
	v_mul_f32_e32 v149, v149, v178
	v_add_f32_dpp v177, v177, v177 quad_perm:[1,0,3,2] row_mask:0xf bank_mask:0xf bound_ctrl:1
	v_mul_f32_e32 v150, v150, v178
	v_mul_f32_e32 v151, v151, v178
	v_add_f32_dpp v177, v177, v177 quad_perm:[2,3,0,1] row_mask:0xf bank_mask:0xf bound_ctrl:1
	v_mul_f32_e32 v18, v18, v148
	v_mul_f32_e32 v19, v19, v149
	v_add_f32_dpp v177, v177, v177 row_half_mirror row_mask:0xf bank_mask:0xf bound_ctrl:1
	v_mul_f32_e32 v20, v20, v150
	v_mul_f32_e32 v21, v21, v151
	v_add_f32_dpp v177, v177, v177 row_mirror row_mask:0xf bank_mask:0xf bound_ctrl:1
	s_lshl_b32 s0, s56, 9
	s_add_u32 s62, s34, s0
	s_addc_u32 s63, s35, 0
	v_mul_f32_e32 v156, v138, v177
	v_mul_f32_e32 v157, v226, v177
	v_mul_f32_e32 v158, v139, v177
	v_mul_f32_e32 v159, v227, v177
	v_cvt_pk_bf16_f32 v72, v134, v222
	v_cvt_pk_bf16_f32 v73, v135, v223
	global_store_dwordx2 v250, v[72:73], s[62:63]
	v_cvt_pk_bf16_f32 v74, v14, v15
	v_cvt_pk_bf16_f32 v75, v16, v17
	s_add_u32 s0, s62, 0x500000
	s_addc_u32 s1, s63, 0
	global_store_dwordx2 v250, v[74:75], s[0:1]
	v_cvt_pk_bf16_f32 v180, v152, v153
	v_cvt_pk_bf16_f32 v181, v154, v155
	s_add_u32 s0, s62, 0xa00000
	s_addc_u32 s1, s63, 0
	global_store_dwordx2 v250, v[180:181], s[0:1]
	v_cvt_pk_bf16_f32 v72, v138, v226
	v_cvt_pk_bf16_f32 v73, v139, v227
	s_add_u32 s0, s62, 0xf00000
	s_addc_u32 s1, s63, 0
	global_store_dwordx2 v250, v[72:73], s[0:1]
	v_cvt_pk_bf16_f32 v74, v148, v149
	v_cvt_pk_bf16_f32 v75, v150, v151
	s_add_u32 s0, s62, 0x1400000
	s_addc_u32 s1, s63, 0
	global_store_dwordx2 v250, v[74:75], s[0:1]
	v_cvt_pk_bf16_f32 v180, v18, v19
	v_cvt_pk_bf16_f32 v181, v20, v21
	s_add_u32 s0, s62, 0x1900000
	s_addc_u32 s1, s63, 0
	global_store_dwordx2 v250, v[180:181], s[0:1]
	v_cvt_pk_bf16_f32 v72, v156, v157
	v_cvt_pk_bf16_f32 v73, v158, v159
	s_lshl_b32 s0, s56, 9
	s_add_u32 s0, s42, s0
	s_addc_u32 s1, s43, 0
	global_store_dwordx2 v250, v[72:73], s[0:1]
	s_add_i32 s56, s53, 12
	s_cmpk_lt_i32 s56, 0x2000
	s_movk_i32 s0, 0x3ff
	s_cselect_b32 s0, 0xff, s0
	s_and_b32 s1, s56, s0
	s_cmp_lg_u32 s1, 0
	s_cselect_b32 s59, 1.0, 0
	s_cselect_b32 s1, -1, 0
	s_add_i32 s1, s56, s1
	s_mul_i32 s0, s56, 0x1d00
	s_add_u32 s76, s28, s0
	s_addc_u32 s77, s29, 0
	s_mul_i32 s0, s1, 0x1d00
	s_add_u32 s78, s28, s0
	s_addc_u32 s79, s29, 0
	global_load_dwordx2 v[222:223], v250, s[76:77] offset:0
	global_load_dwordx2 v[224:225], v250, s[76:77] offset:512
	global_load_dwordx2 v[226:227], v250, s[76:77] offset:1024
	global_load_dwordx2 v[228:229], v250, s[78:79] offset:0
	global_load_dwordx2 v[230:231], v250, s[78:79] offset:512
	global_load_dwordx2 v[232:233], v250, s[78:79] offset:1024
	ds_read_b128 v[14:17], v31 offset:8192
	ds_read_b128 v[18:21], v31 offset:28672
	s_waitcnt vmcnt(19)
	v_lshlrev_b32_e32 v134, 16, v236
	v_and_b32_e32 v236, 0xffff0000, v236
	v_lshlrev_b32_e32 v135, 16, v237
	v_and_b32_e32 v237, 0xffff0000, v237
	v_lshlrev_b32_e32 v136, 16, v238
	v_and_b32_e32 v238, 0xffff0000, v238
	v_lshlrev_b32_e32 v137, 16, v239
	v_and_b32_e32 v239, 0xffff0000, v239
	v_lshlrev_b32_e32 v138, 16, v240
	v_and_b32_e32 v240, 0xffff0000, v240
	v_lshlrev_b32_e32 v139, 16, v241
	v_and_b32_e32 v241, 0xffff0000, v241
	v_lshlrev_b32_e32 v140, 16, v242
	v_and_b32_e32 v242, 0xffff0000, v242
	v_lshlrev_b32_e32 v141, 16, v243
	v_and_b32_e32 v243, 0xffff0000, v243
	v_lshlrev_b32_e32 v142, 16, v244
	v_and_b32_e32 v244, 0xffff0000, v244
	v_lshlrev_b32_e32 v143, 16, v245
	v_and_b32_e32 v245, 0xffff0000, v245
	v_lshlrev_b32_e32 v144, 16, v246
	v_and_b32_e32 v246, 0xffff0000, v246
	v_lshlrev_b32_e32 v145, 16, v247
	v_and_b32_e32 v247, 0xffff0000, v247
	v_fma_f32 v140, s60, v140, -v134
	v_fma_f32 v242, s60, v242, -v236
	v_fma_f32 v141, s60, v141, -v135
	v_fma_f32 v243, s60, v243, -v237
	v_fmac_f32_e32 v134, v210, v140
	v_fmac_f32_e32 v236, v211, v242
	v_fmac_f32_e32 v135, v212, v141
	v_fmac_f32_e32 v237, v213, v243
	v_fma_f32 v142, s60, v142, -v136
	v_fma_f32 v244, s60, v244, -v238
	v_fma_f32 v143, s60, v143, -v137
	v_fma_f32 v245, s60, v245, -v239
	v_fmac_f32_e32 v136, v214, v142
	v_fmac_f32_e32 v238, v215, v244
	v_fmac_f32_e32 v137, v216, v143
	v_fmac_f32_e32 v239, v217, v245
	v_fma_f32 v144, s60, v144, -v138
	v_fma_f32 v246, s60, v246, -v240
	v_fma_f32 v145, s60, v145, -v139
	v_fma_f32 v247, s60, v247, -v241
	v_fmac_f32_e32 v138, v218, v144
	v_fmac_f32_e32 v240, v219, v246
	v_fmac_f32_e32 v139, v220, v145
	v_fmac_f32_e32 v241, v221, v247
	v_mul_f32_e32 v148, v198, v136
	v_mul_f32_e32 v149, v199, v238
	v_mul_f32_e32 v150, v200, v137
	v_mul_f32_e32 v151, v201, v239
	v_mul_f32_e32 v176, v148, v148
	v_fmac_f32_e32 v176, v149, v149
	v_fmac_f32_e32 v176, v150, v150
	v_fmac_f32_e32 v176, v151, v151
	s_waitcnt lgkmcnt(2)
	v_add_f32_e32 v26, v194, v26
	v_add_f32_e32 v27, v195, v27
	v_add_f32_e32 v28, v196, v28
	v_add_f32_e32 v29, v197, v29
	v_add_f32_dpp v176, v176, v176 quad_perm:[1,0,3,2] row_mask:0xf bank_mask:0xf bound_ctrl:1
	v_mul_f32_e32 v26, 0xbfb8aa3b, v26
	v_mul_f32_e32 v27, 0xbfb8aa3b, v27
	v_mul_f32_e32 v28, 0xbfb8aa3b, v28
	v_mul_f32_e32 v29, 0xbfb8aa3b, v29
	v_add_f32_dpp v176, v176, v176 quad_perm:[2,3,0,1] row_mask:0xf bank_mask:0xf bound_ctrl:1
	v_exp_f32_e32 v26, v26
	v_exp_f32_e32 v27, v27
	v_exp_f32_e32 v28, v28
	v_exp_f32_e32 v29, v29
	v_add_f32_dpp v176, v176, v176 row_half_mirror row_mask:0xf bank_mask:0xf bound_ctrl:1
	v_add_f32_e32 v26, 1.0, v26
	v_add_f32_e32 v27, 1.0, v27
	v_add_f32_e32 v28, 1.0, v28
	v_add_f32_e32 v29, 1.0, v29
	v_add_f32_dpp v176, v176, v176 row_mirror row_mask:0xf bank_mask:0xf bound_ctrl:1
	v_rcp_f32_e32 v26, v26
	v_rcp_f32_e32 v27, v27
	v_rcp_f32_e32 v28, v28
	v_rcp_f32_e32 v29, v29
	v_sqrt_f32_e32 v176, v176
	v_add_f32_e32 v22, v190, v22
	v_add_f32_e32 v23, v191, v23
	v_add_f32_e32 v24, v192, v24
	v_add_f32_e32 v25, v193, v25
	v_max_f32_e32 v176, 0x2b8cbccc, v176
	v_mul_f32_e32 v22, 0xbfb8aa3b, v22
	v_mul_f32_e32 v23, 0xbfb8aa3b, v23
	v_mul_f32_e32 v24, 0xbfb8aa3b, v24
	v_mul_f32_e32 v25, 0xbfb8aa3b, v25
	v_rcp_f32_e32 v178, v176
	v_exp_f32_e32 v22, v22
	v_exp_f32_e32 v23, v23
	v_exp_f32_e32 v24, v24
	v_exp_f32_e32 v25, v25
	v_add_f32_e32 v22, 1.0, v22
	v_add_f32_e32 v23, 1.0, v23
	v_add_f32_e32 v24, 1.0, v24
	v_add_f32_e32 v25, 1.0, v25
	v_rcp_f32_e32 v22, v22
	v_rcp_f32_e32 v23, v23
	v_rcp_f32_e32 v24, v24
	v_rcp_f32_e32 v25, v25
	v_mul_f32_e32 v22, 0xbf1b4598, v22
	v_mul_f32_e32 v23, 0xbf1b4598, v23
	v_mul_f32_e32 v24, 0xbf1b4598, v24
	v_mul_f32_e32 v25, 0xbf1b4598, v25
	v_mul_f32_e32 v22, 0x3fb8aa3b, v22
	v_mul_f32_e32 v23, 0x3fb8aa3b, v23
	v_mul_f32_e32 v24, 0x3fb8aa3b, v24
	v_mul_f32_e32 v25, 0x3fb8aa3b, v25
	v_exp_f32_e32 v22, v22
	v_exp_f32_e32 v23, v23
	v_exp_f32_e32 v24, v24
	v_exp_f32_e32 v25, v25
	v_add_f32_e32 v152, -1.0, v26
	v_add_f32_e32 v153, -1.0, v27
	v_add_f32_e32 v154, -1.0, v28
	v_add_f32_e32 v155, -1.0, v29
	v_fma_f32 v152, v202, v152, 1.0
	v_fma_f32 v153, v203, v153, 1.0
	v_fma_f32 v154, v204, v154, 1.0
	v_fma_f32 v155, v205, v155, 1.0
	v_mul_f32_e32 v152, v136, v152
	v_mul_f32_e32 v153, v238, v153
	v_mul_f32_e32 v154, v137, v154
	v_mul_f32_e32 v155, v239, v155
	v_mul_f32_e32 v156, v134, v152
	v_mul_f32_e32 v157, v236, v153
	v_mul_f32_e32 v158, v135, v154
	v_mul_f32_e32 v159, v237, v155
	v_mul_f32_e32 v177, v206, v156
	v_fmac_f32_e32 v177, v207, v157
	v_fmac_f32_e32 v177, v208, v158
	v_fmac_f32_e32 v177, v209, v159
	v_mul_f32_e32 v148, v148, v178
	v_mul_f32_e32 v149, v149, v178
	v_add_f32_dpp v177, v177, v177 quad_perm:[1,0,3,2] row_mask:0xf bank_mask:0xf bound_ctrl:1
	v_mul_f32_e32 v150, v150, v178
	v_mul_f32_e32 v151, v151, v178
	v_add_f32_dpp v177, v177, v177 quad_perm:[2,3,0,1] row_mask:0xf bank_mask:0xf bound_ctrl:1
	v_mul_f32_e32 v26, v26, v148
	v_mul_f32_e32 v27, v27, v149
	v_add_f32_dpp v177, v177, v177 row_half_mirror row_mask:0xf bank_mask:0xf bound_ctrl:1
	v_mul_f32_e32 v28, v28, v150
	v_mul_f32_e32 v29, v29, v151
	v_add_f32_dpp v177, v177, v177 row_mirror row_mask:0xf bank_mask:0xf bound_ctrl:1
	s_lshl_b32 s0, s57, 9
	s_add_u32 s62, s34, s0
	s_addc_u32 s63, s35, 0
	v_mul_f32_e32 v156, v138, v177
	v_mul_f32_e32 v157, v240, v177
	v_mul_f32_e32 v158, v139, v177
	v_mul_f32_e32 v159, v241, v177
	v_cvt_pk_bf16_f32 v72, v134, v236
	v_cvt_pk_bf16_f32 v73, v135, v237
	global_store_dwordx2 v250, v[72:73], s[62:63]
	v_cvt_pk_bf16_f32 v74, v22, v23
	v_cvt_pk_bf16_f32 v75, v24, v25
	s_add_u32 s0, s62, 0x500000
	s_addc_u32 s1, s63, 0
	global_store_dwordx2 v250, v[74:75], s[0:1]
	v_cvt_pk_bf16_f32 v180, v152, v153
	v_cvt_pk_bf16_f32 v181, v154, v155
	s_add_u32 s0, s62, 0xa00000
	s_addc_u32 s1, s63, 0
	global_store_dwordx2 v250, v[180:181], s[0:1]
	v_cvt_pk_bf16_f32 v72, v138, v240
	v_cvt_pk_bf16_f32 v73, v139, v241
	s_add_u32 s0, s62, 0xf00000
	s_addc_u32 s1, s63, 0
	global_store_dwordx2 v250, v[72:73], s[0:1]
	v_cvt_pk_bf16_f32 v74, v148, v149
	v_cvt_pk_bf16_f32 v75, v150, v151
	s_add_u32 s0, s62, 0x1400000
	s_addc_u32 s1, s63, 0
	global_store_dwordx2 v250, v[74:75], s[0:1]
	v_cvt_pk_bf16_f32 v180, v26, v27
	v_cvt_pk_bf16_f32 v181, v28, v29
	s_add_u32 s0, s62, 0x1900000
	s_addc_u32 s1, s63, 0
	global_store_dwordx2 v250, v[180:181], s[0:1]
	v_cvt_pk_bf16_f32 v72, v156, v157
	v_cvt_pk_bf16_f32 v73, v158, v159
	s_lshl_b32 s0, s57, 9
	s_add_u32 s0, s42, s0
	s_addc_u32 s1, s43, 0
	global_store_dwordx2 v250, v[72:73], s[0:1]
	s_add_i32 s57, s53, 16
	s_cmpk_lt_i32 s57, 0x2000
	s_movk_i32 s0, 0x3ff
	s_cselect_b32 s0, 0xff, s0
	s_and_b32 s1, s57, s0
	s_cmp_lg_u32 s1, 0
	s_cselect_b32 s60, 1.0, 0
	s_cselect_b32 s1, -1, 0
	s_add_i32 s1, s57, s1
	s_mul_i32 s0, s57, 0x1d00
	s_add_u32 s80, s28, s0
	s_addc_u32 s81, s29, 0
	s_mul_i32 s0, s1, 0x1d00
	s_add_u32 s82, s28, s0
	s_addc_u32 s83, s29, 0
	global_load_dwordx2 v[236:237], v250, s[80:81] offset:0
	global_load_dwordx2 v[238:239], v250, s[80:81] offset:512
	global_load_dwordx2 v[240:241], v250, s[80:81] offset:1024
	global_load_dwordx2 v[242:243], v250, s[82:83] offset:0
	global_load_dwordx2 v[244:245], v250, s[82:83] offset:512
	global_load_dwordx2 v[246:247], v250, s[82:83] offset:1024
	ds_read_b128 v[22:25], v31 offset:12288
	ds_read_b128 v[26:29], v31 offset:32768
	s_waitcnt vmcnt(26)
	v_lshlrev_b32_e32 v134, 16, v0
	v_and_b32_e32 v0, 0xffff0000, v0
	v_lshlrev_b32_e32 v135, 16, v1
	v_and_b32_e32 v1, 0xffff0000, v1
	v_lshlrev_b32_e32 v136, 16, v2
	v_and_b32_e32 v2, 0xffff0000, v2
	v_lshlrev_b32_e32 v137, 16, v3
	v_and_b32_e32 v3, 0xffff0000, v3
	v_lshlrev_b32_e32 v138, 16, v4
	v_and_b32_e32 v4, 0xffff0000, v4
	v_lshlrev_b32_e32 v139, 16, v5
	v_and_b32_e32 v5, 0xffff0000, v5
	v_lshlrev_b32_e32 v140, 16, v6
	v_and_b32_e32 v6, 0xffff0000, v6
	v_lshlrev_b32_e32 v141, 16, v7
	v_and_b32_e32 v7, 0xffff0000, v7
	v_lshlrev_b32_e32 v142, 16, v8
	v_and_b32_e32 v8, 0xffff0000, v8
	v_lshlrev_b32_e32 v143, 16, v9
	v_and_b32_e32 v9, 0xffff0000, v9
	v_lshlrev_b32_e32 v144, 16, v10
	v_and_b32_e32 v10, 0xffff0000, v10
	v_lshlrev_b32_e32 v145, 16, v11
	v_and_b32_e32 v11, 0xffff0000, v11
	v_fma_f32 v140, s61, v140, -v134
	v_fma_f32 v6, s61, v6, -v0
	v_fma_f32 v141, s61, v141, -v135
	v_fma_f32 v7, s61, v7, -v1
	v_fmac_f32_e32 v134, v210, v140
	v_fmac_f32_e32 v0, v211, v6
	v_fmac_f32_e32 v135, v212, v141
	v_fmac_f32_e32 v1, v213, v7
	v_fma_f32 v142, s61, v142, -v136
	v_fma_f32 v8, s61, v8, -v2
	v_fma_f32 v143, s61, v143, -v137
	v_fma_f32 v9, s61, v9, -v3
	v_fmac_f32_e32 v136, v214, v142
	v_fmac_f32_e32 v2, v215, v8
	v_fmac_f32_e32 v137, v216, v143
	v_fmac_f32_e32 v3, v217, v9
	v_fma_f32 v144, s61, v144, -v138
	v_fma_f32 v10, s61, v10, -v4
	v_fma_f32 v145, s61, v145, -v139
	v_fma_f32 v11, s61, v11, -v5
	v_fmac_f32_e32 v138, v218, v144
	v_fmac_f32_e32 v4, v219, v10
	v_fmac_f32_e32 v139, v220, v145
	v_fmac_f32_e32 v5, v221, v11
	v_mul_f32_e32 v148, v198, v136
	v_mul_f32_e32 v149, v199, v2
	v_mul_f32_e32 v150, v200, v137
	v_mul_f32_e32 v151, v201, v3
	v_mul_f32_e32 v176, v148, v148
	v_fmac_f32_e32 v176, v149, v149
	v_fmac_f32_e32 v176, v150, v150
	v_fmac_f32_e32 v176, v151, v151
	s_waitcnt lgkmcnt(2)
	v_add_f32_e32 v18, v194, v18
	v_add_f32_e32 v19, v195, v19
	v_add_f32_e32 v20, v196, v20
	v_add_f32_e32 v21, v197, v21
	v_add_f32_dpp v176, v176, v176 quad_perm:[1,0,3,2] row_mask:0xf bank_mask:0xf bound_ctrl:1
	v_mul_f32_e32 v18, 0xbfb8aa3b, v18
	v_mul_f32_e32 v19, 0xbfb8aa3b, v19
	v_mul_f32_e32 v20, 0xbfb8aa3b, v20
	v_mul_f32_e32 v21, 0xbfb8aa3b, v21
	v_add_f32_dpp v176, v176, v176 quad_perm:[2,3,0,1] row_mask:0xf bank_mask:0xf bound_ctrl:1
	v_exp_f32_e32 v18, v18
	v_exp_f32_e32 v19, v19
	v_exp_f32_e32 v20, v20
	v_exp_f32_e32 v21, v21
	v_add_f32_dpp v176, v176, v176 row_half_mirror row_mask:0xf bank_mask:0xf bound_ctrl:1
	v_add_f32_e32 v18, 1.0, v18
	v_add_f32_e32 v19, 1.0, v19
	v_add_f32_e32 v20, 1.0, v20
	v_add_f32_e32 v21, 1.0, v21
	v_add_f32_dpp v176, v176, v176 row_mirror row_mask:0xf bank_mask:0xf bound_ctrl:1
	v_rcp_f32_e32 v18, v18
	v_rcp_f32_e32 v19, v19
	v_rcp_f32_e32 v20, v20
	v_rcp_f32_e32 v21, v21
	v_sqrt_f32_e32 v176, v176
	v_add_f32_e32 v14, v190, v14
	v_add_f32_e32 v15, v191, v15
	v_add_f32_e32 v16, v192, v16
	v_add_f32_e32 v17, v193, v17
	v_max_f32_e32 v176, 0x2b8cbccc, v176
	v_mul_f32_e32 v14, 0xbfb8aa3b, v14
	v_mul_f32_e32 v15, 0xbfb8aa3b, v15
	v_mul_f32_e32 v16, 0xbfb8aa3b, v16
	v_mul_f32_e32 v17, 0xbfb8aa3b, v17
	v_rcp_f32_e32 v178, v176
	v_exp_f32_e32 v14, v14
	v_exp_f32_e32 v15, v15
	v_exp_f32_e32 v16, v16
	v_exp_f32_e32 v17, v17
	v_add_f32_e32 v14, 1.0, v14
	v_add_f32_e32 v15, 1.0, v15
	v_add_f32_e32 v16, 1.0, v16
	v_add_f32_e32 v17, 1.0, v17
	v_rcp_f32_e32 v14, v14
	v_rcp_f32_e32 v15, v15
	v_rcp_f32_e32 v16, v16
	v_rcp_f32_e32 v17, v17
	v_mul_f32_e32 v14, 0xbf1b4598, v14
	v_mul_f32_e32 v15, 0xbf1b4598, v15
	v_mul_f32_e32 v16, 0xbf1b4598, v16
	v_mul_f32_e32 v17, 0xbf1b4598, v17
	v_mul_f32_e32 v14, 0x3fb8aa3b, v14
	v_mul_f32_e32 v15, 0x3fb8aa3b, v15
	v_mul_f32_e32 v16, 0x3fb8aa3b, v16
	v_mul_f32_e32 v17, 0x3fb8aa3b, v17
	v_exp_f32_e32 v14, v14
	v_exp_f32_e32 v15, v15
	v_exp_f32_e32 v16, v16
	v_exp_f32_e32 v17, v17
	v_add_f32_e32 v152, -1.0, v18
	v_add_f32_e32 v153, -1.0, v19
	v_add_f32_e32 v154, -1.0, v20
	v_add_f32_e32 v155, -1.0, v21
	v_fma_f32 v152, v202, v152, 1.0
	v_fma_f32 v153, v203, v153, 1.0
	v_fma_f32 v154, v204, v154, 1.0
	v_fma_f32 v155, v205, v155, 1.0
	v_mul_f32_e32 v152, v136, v152
	v_mul_f32_e32 v153, v2, v153
	v_mul_f32_e32 v154, v137, v154
	v_mul_f32_e32 v155, v3, v155
	v_mul_f32_e32 v156, v134, v152
	v_mul_f32_e32 v157, v0, v153
	v_mul_f32_e32 v158, v135, v154
	v_mul_f32_e32 v159, v1, v155
	v_mul_f32_e32 v177, v206, v156
	v_fmac_f32_e32 v177, v207, v157
	v_fmac_f32_e32 v177, v208, v158
	v_fmac_f32_e32 v177, v209, v159
	v_mul_f32_e32 v148, v148, v178
	v_mul_f32_e32 v149, v149, v178
	v_add_f32_dpp v177, v177, v177 quad_perm:[1,0,3,2] row_mask:0xf bank_mask:0xf bound_ctrl:1
	v_mul_f32_e32 v150, v150, v178
	v_mul_f32_e32 v151, v151, v178
	v_add_f32_dpp v177, v177, v177 quad_perm:[2,3,0,1] row_mask:0xf bank_mask:0xf bound_ctrl:1
	v_mul_f32_e32 v18, v18, v148
	v_mul_f32_e32 v19, v19, v149
	v_add_f32_dpp v177, v177, v177 row_half_mirror row_mask:0xf bank_mask:0xf bound_ctrl:1
	v_mul_f32_e32 v20, v20, v150
	v_mul_f32_e32 v21, v21, v151
	v_add_f32_dpp v177, v177, v177 row_mirror row_mask:0xf bank_mask:0xf bound_ctrl:1
	s_lshl_b32 s0, s58, 9
	s_add_u32 s62, s34, s0
	s_addc_u32 s63, s35, 0
	v_mul_f32_e32 v156, v138, v177
	v_mul_f32_e32 v157, v4, v177
	v_mul_f32_e32 v158, v139, v177
	v_mul_f32_e32 v159, v5, v177
	v_cvt_pk_bf16_f32 v72, v134, v0
	v_cvt_pk_bf16_f32 v73, v135, v1
	global_store_dwordx2 v250, v[72:73], s[62:63]
	v_cvt_pk_bf16_f32 v74, v14, v15
	v_cvt_pk_bf16_f32 v75, v16, v17
	s_add_u32 s0, s62, 0x500000
	s_addc_u32 s1, s63, 0
	global_store_dwordx2 v250, v[74:75], s[0:1]
	v_cvt_pk_bf16_f32 v180, v152, v153
	v_cvt_pk_bf16_f32 v181, v154, v155
	s_add_u32 s0, s62, 0xa00000
	s_addc_u32 s1, s63, 0
	global_store_dwordx2 v250, v[180:181], s[0:1]
	v_cvt_pk_bf16_f32 v72, v138, v4
	v_cvt_pk_bf16_f32 v73, v139, v5
	s_add_u32 s0, s62, 0xf00000
	s_addc_u32 s1, s63, 0
	global_store_dwordx2 v250, v[72:73], s[0:1]
	v_cvt_pk_bf16_f32 v74, v148, v149
	v_cvt_pk_bf16_f32 v75, v150, v151
	s_add_u32 s0, s62, 0x1400000
	s_addc_u32 s1, s63, 0
	global_store_dwordx2 v250, v[74:75], s[0:1]
	v_cvt_pk_bf16_f32 v180, v18, v19
	v_cvt_pk_bf16_f32 v181, v20, v21
	s_add_u32 s0, s62, 0x1900000
	s_addc_u32 s1, s63, 0
	global_store_dwordx2 v250, v[180:181], s[0:1]
	v_cvt_pk_bf16_f32 v72, v156, v157
	v_cvt_pk_bf16_f32 v73, v158, v159
	s_lshl_b32 s0, s58, 9
	s_add_u32 s0, s42, s0
	s_addc_u32 s1, s43, 0
	global_store_dwordx2 v250, v[72:73], s[0:1]
	ds_read_b128 v[14:17], v31 offset:16384
	ds_read_b128 v[18:21], v31 offset:36864
	s_waitcnt vmcnt(20)
	v_lshlrev_b32_e32 v134, 16, v222
	v_and_b32_e32 v222, 0xffff0000, v222
	v_lshlrev_b32_e32 v135, 16, v223
	v_and_b32_e32 v223, 0xffff0000, v223
	v_lshlrev_b32_e32 v136, 16, v224
	v_and_b32_e32 v224, 0xffff0000, v224
	v_lshlrev_b32_e32 v137, 16, v225
	v_and_b32_e32 v225, 0xffff0000, v225
	v_lshlrev_b32_e32 v138, 16, v226
	v_and_b32_e32 v226, 0xffff0000, v226
	v_lshlrev_b32_e32 v139, 16, v227
	v_and_b32_e32 v227, 0xffff0000, v227
	v_lshlrev_b32_e32 v140, 16, v228
	v_and_b32_e32 v228, 0xffff0000, v228
	v_lshlrev_b32_e32 v141, 16, v229
	v_and_b32_e32 v229, 0xffff0000, v229
	v_lshlrev_b32_e32 v142, 16, v230
	v_and_b32_e32 v230, 0xffff0000, v230
	v_lshlrev_b32_e32 v143, 16, v231
	v_and_b32_e32 v231, 0xffff0000, v231
	v_lshlrev_b32_e32 v144, 16, v232
	v_and_b32_e32 v232, 0xffff0000, v232
	v_lshlrev_b32_e32 v145, 16, v233
	v_and_b32_e32 v233, 0xffff0000, v233
	v_fma_f32 v140, s59, v140, -v134
	v_fma_f32 v228, s59, v228, -v222
	v_fma_f32 v141, s59, v141, -v135
	v_fma_f32 v229, s59, v229, -v223
	v_fmac_f32_e32 v134, v210, v140
	v_fmac_f32_e32 v222, v211, v228
	v_fmac_f32_e32 v135, v212, v141
	v_fmac_f32_e32 v223, v213, v229
	v_fma_f32 v142, s59, v142, -v136
	v_fma_f32 v230, s59, v230, -v224
	v_fma_f32 v143, s59, v143, -v137
	v_fma_f32 v231, s59, v231, -v225
	v_fmac_f32_e32 v136, v214, v142
	v_fmac_f32_e32 v224, v215, v230
	v_fmac_f32_e32 v137, v216, v143
	v_fmac_f32_e32 v225, v217, v231
	v_fma_f32 v144, s59, v144, -v138
	v_fma_f32 v232, s59, v232, -v226
	v_fma_f32 v145, s59, v145, -v139
	v_fma_f32 v233, s59, v233, -v227
	v_fmac_f32_e32 v138, v218, v144
	v_fmac_f32_e32 v226, v219, v232
	v_fmac_f32_e32 v139, v220, v145
	v_fmac_f32_e32 v227, v221, v233
	v_mul_f32_e32 v148, v198, v136
	v_mul_f32_e32 v149, v199, v224
	v_mul_f32_e32 v150, v200, v137
	v_mul_f32_e32 v151, v201, v225
	v_mul_f32_e32 v176, v148, v148
	v_fmac_f32_e32 v176, v149, v149
	v_fmac_f32_e32 v176, v150, v150
	v_fmac_f32_e32 v176, v151, v151
	s_waitcnt lgkmcnt(2)
	v_add_f32_e32 v26, v194, v26
	v_add_f32_e32 v27, v195, v27
	v_add_f32_e32 v28, v196, v28
	v_add_f32_e32 v29, v197, v29
	v_add_f32_dpp v176, v176, v176 quad_perm:[1,0,3,2] row_mask:0xf bank_mask:0xf bound_ctrl:1
	v_mul_f32_e32 v26, 0xbfb8aa3b, v26
	v_mul_f32_e32 v27, 0xbfb8aa3b, v27
	v_mul_f32_e32 v28, 0xbfb8aa3b, v28
	v_mul_f32_e32 v29, 0xbfb8aa3b, v29
	v_add_f32_dpp v176, v176, v176 quad_perm:[2,3,0,1] row_mask:0xf bank_mask:0xf bound_ctrl:1
	v_exp_f32_e32 v26, v26
	v_exp_f32_e32 v27, v27
	v_exp_f32_e32 v28, v28
	v_exp_f32_e32 v29, v29
	v_add_f32_dpp v176, v176, v176 row_half_mirror row_mask:0xf bank_mask:0xf bound_ctrl:1
	v_add_f32_e32 v26, 1.0, v26
	v_add_f32_e32 v27, 1.0, v27
	v_add_f32_e32 v28, 1.0, v28
	v_add_f32_e32 v29, 1.0, v29
	v_add_f32_dpp v176, v176, v176 row_mirror row_mask:0xf bank_mask:0xf bound_ctrl:1
	v_rcp_f32_e32 v26, v26
	v_rcp_f32_e32 v27, v27
	v_rcp_f32_e32 v28, v28
	v_rcp_f32_e32 v29, v29
	v_sqrt_f32_e32 v176, v176
	v_add_f32_e32 v22, v190, v22
	v_add_f32_e32 v23, v191, v23
	v_add_f32_e32 v24, v192, v24
	v_add_f32_e32 v25, v193, v25
	v_max_f32_e32 v176, 0x2b8cbccc, v176
	v_mul_f32_e32 v22, 0xbfb8aa3b, v22
	v_mul_f32_e32 v23, 0xbfb8aa3b, v23
	v_mul_f32_e32 v24, 0xbfb8aa3b, v24
	v_mul_f32_e32 v25, 0xbfb8aa3b, v25
	v_rcp_f32_e32 v178, v176
	v_exp_f32_e32 v22, v22
	v_exp_f32_e32 v23, v23
	v_exp_f32_e32 v24, v24
	v_exp_f32_e32 v25, v25
	v_add_f32_e32 v22, 1.0, v22
	v_add_f32_e32 v23, 1.0, v23
	v_add_f32_e32 v24, 1.0, v24
	v_add_f32_e32 v25, 1.0, v25
	v_rcp_f32_e32 v22, v22
	v_rcp_f32_e32 v23, v23
	v_rcp_f32_e32 v24, v24
	v_rcp_f32_e32 v25, v25
	v_mul_f32_e32 v22, 0xbf1b4598, v22
	v_mul_f32_e32 v23, 0xbf1b4598, v23
	v_mul_f32_e32 v24, 0xbf1b4598, v24
	v_mul_f32_e32 v25, 0xbf1b4598, v25
	v_mul_f32_e32 v22, 0x3fb8aa3b, v22
	v_mul_f32_e32 v23, 0x3fb8aa3b, v23
	v_mul_f32_e32 v24, 0x3fb8aa3b, v24
	v_mul_f32_e32 v25, 0x3fb8aa3b, v25
	v_exp_f32_e32 v22, v22
	v_exp_f32_e32 v23, v23
	v_exp_f32_e32 v24, v24
	v_exp_f32_e32 v25, v25
	v_add_f32_e32 v152, -1.0, v26
	v_add_f32_e32 v153, -1.0, v27
	v_add_f32_e32 v154, -1.0, v28
	v_add_f32_e32 v155, -1.0, v29
	v_fma_f32 v152, v202, v152, 1.0
	v_fma_f32 v153, v203, v153, 1.0
	v_fma_f32 v154, v204, v154, 1.0
	v_fma_f32 v155, v205, v155, 1.0
	v_mul_f32_e32 v152, v136, v152
	v_mul_f32_e32 v153, v224, v153
	v_mul_f32_e32 v154, v137, v154
	v_mul_f32_e32 v155, v225, v155
	v_mul_f32_e32 v156, v134, v152
	v_mul_f32_e32 v157, v222, v153
	v_mul_f32_e32 v158, v135, v154
	v_mul_f32_e32 v159, v223, v155
	v_mul_f32_e32 v177, v206, v156
	v_fmac_f32_e32 v177, v207, v157
	v_fmac_f32_e32 v177, v208, v158
	v_fmac_f32_e32 v177, v209, v159
	v_mul_f32_e32 v148, v148, v178
	v_mul_f32_e32 v149, v149, v178
	v_add_f32_dpp v177, v177, v177 quad_perm:[1,0,3,2] row_mask:0xf bank_mask:0xf bound_ctrl:1
	v_mul_f32_e32 v150, v150, v178
	v_mul_f32_e32 v151, v151, v178
	v_add_f32_dpp v177, v177, v177 quad_perm:[2,3,0,1] row_mask:0xf bank_mask:0xf bound_ctrl:1
	v_mul_f32_e32 v26, v26, v148
	v_mul_f32_e32 v27, v27, v149
	v_add_f32_dpp v177, v177, v177 row_half_mirror row_mask:0xf bank_mask:0xf bound_ctrl:1
	v_mul_f32_e32 v28, v28, v150
	v_mul_f32_e32 v29, v29, v151
	v_add_f32_dpp v177, v177, v177 row_mirror row_mask:0xf bank_mask:0xf bound_ctrl:1
	s_lshl_b32 s0, s56, 9
	s_add_u32 s62, s34, s0
	s_addc_u32 s63, s35, 0
	v_mul_f32_e32 v156, v138, v177
	v_mul_f32_e32 v157, v226, v177
	v_mul_f32_e32 v158, v139, v177
	v_mul_f32_e32 v159, v227, v177
	v_cvt_pk_bf16_f32 v72, v134, v222
	v_cvt_pk_bf16_f32 v73, v135, v223
	global_store_dwordx2 v250, v[72:73], s[62:63]
	v_cvt_pk_bf16_f32 v74, v22, v23
	v_cvt_pk_bf16_f32 v75, v24, v25
	s_add_u32 s0, s62, 0x500000
	s_addc_u32 s1, s63, 0
	global_store_dwordx2 v250, v[74:75], s[0:1]
	v_cvt_pk_bf16_f32 v180, v152, v153
	v_cvt_pk_bf16_f32 v181, v154, v155
	s_add_u32 s0, s62, 0xa00000
	s_addc_u32 s1, s63, 0
	global_store_dwordx2 v250, v[180:181], s[0:1]
	v_cvt_pk_bf16_f32 v72, v138, v226
	v_cvt_pk_bf16_f32 v73, v139, v227
	s_add_u32 s0, s62, 0xf00000
	s_addc_u32 s1, s63, 0
	global_store_dwordx2 v250, v[72:73], s[0:1]
	v_cvt_pk_bf16_f32 v74, v148, v149
	v_cvt_pk_bf16_f32 v75, v150, v151
	s_add_u32 s0, s62, 0x1400000
	s_addc_u32 s1, s63, 0
	global_store_dwordx2 v250, v[74:75], s[0:1]
	v_cvt_pk_bf16_f32 v180, v26, v27
	v_cvt_pk_bf16_f32 v181, v28, v29
	s_add_u32 s0, s62, 0x1900000
	s_addc_u32 s1, s63, 0
	global_store_dwordx2 v250, v[180:181], s[0:1]
	v_cvt_pk_bf16_f32 v72, v156, v157
	v_cvt_pk_bf16_f32 v73, v158, v159
	s_lshl_b32 s0, s56, 9
	s_add_u32 s0, s42, s0
	s_addc_u32 s1, s43, 0
	global_store_dwordx2 v250, v[72:73], s[0:1]
	s_waitcnt vmcnt(14)
	v_lshlrev_b32_e32 v134, 16, v236
	v_and_b32_e32 v236, 0xffff0000, v236
	v_lshlrev_b32_e32 v135, 16, v237
	v_and_b32_e32 v237, 0xffff0000, v237
	v_lshlrev_b32_e32 v136, 16, v238
	v_and_b32_e32 v238, 0xffff0000, v238
	v_lshlrev_b32_e32 v137, 16, v239
	v_and_b32_e32 v239, 0xffff0000, v239
	v_lshlrev_b32_e32 v138, 16, v240
	v_and_b32_e32 v240, 0xffff0000, v240
	v_lshlrev_b32_e32 v139, 16, v241
	v_and_b32_e32 v241, 0xffff0000, v241
	v_lshlrev_b32_e32 v140, 16, v242
	v_and_b32_e32 v242, 0xffff0000, v242
	v_lshlrev_b32_e32 v141, 16, v243
	v_and_b32_e32 v243, 0xffff0000, v243
	v_lshlrev_b32_e32 v142, 16, v244
	v_and_b32_e32 v244, 0xffff0000, v244
	v_lshlrev_b32_e32 v143, 16, v245
	v_and_b32_e32 v245, 0xffff0000, v245
	v_lshlrev_b32_e32 v144, 16, v246
	v_and_b32_e32 v246, 0xffff0000, v246
	v_lshlrev_b32_e32 v145, 16, v247
	v_and_b32_e32 v247, 0xffff0000, v247
	v_fma_f32 v140, s60, v140, -v134
	v_fma_f32 v242, s60, v242, -v236
	v_fma_f32 v141, s60, v141, -v135
	v_fma_f32 v243, s60, v243, -v237
	v_fmac_f32_e32 v134, v210, v140
	v_fmac_f32_e32 v236, v211, v242
	v_fmac_f32_e32 v135, v212, v141
	v_fmac_f32_e32 v237, v213, v243
	v_fma_f32 v142, s60, v142, -v136
	v_fma_f32 v244, s60, v244, -v238
	v_fma_f32 v143, s60, v143, -v137
	v_fma_f32 v245, s60, v245, -v239
	v_fmac_f32_e32 v136, v214, v142
	v_fmac_f32_e32 v238, v215, v244
	v_fmac_f32_e32 v137, v216, v143
	v_fmac_f32_e32 v239, v217, v245
	v_fma_f32 v144, s60, v144, -v138
	v_fma_f32 v246, s60, v246, -v240
	v_fma_f32 v145, s60, v145, -v139
	v_fma_f32 v247, s60, v247, -v241
	v_fmac_f32_e32 v138, v218, v144
	v_fmac_f32_e32 v240, v219, v246
	v_fmac_f32_e32 v139, v220, v145
	v_fmac_f32_e32 v241, v221, v247
	v_mul_f32_e32 v148, v198, v136
	v_mul_f32_e32 v149, v199, v238
	v_mul_f32_e32 v150, v200, v137
	v_mul_f32_e32 v151, v201, v239
	v_mul_f32_e32 v176, v148, v148
	v_fmac_f32_e32 v176, v149, v149
	v_fmac_f32_e32 v176, v150, v150
	v_fmac_f32_e32 v176, v151, v151
	s_waitcnt lgkmcnt(0)
	v_add_f32_e32 v18, v194, v18
	v_add_f32_e32 v19, v195, v19
	v_add_f32_e32 v20, v196, v20
	v_add_f32_e32 v21, v197, v21
	v_add_f32_dpp v176, v176, v176 quad_perm:[1,0,3,2] row_mask:0xf bank_mask:0xf bound_ctrl:1
	v_mul_f32_e32 v18, 0xbfb8aa3b, v18
	v_mul_f32_e32 v19, 0xbfb8aa3b, v19
	v_mul_f32_e32 v20, 0xbfb8aa3b, v20
	v_mul_f32_e32 v21, 0xbfb8aa3b, v21
	v_add_f32_dpp v176, v176, v176 quad_perm:[2,3,0,1] row_mask:0xf bank_mask:0xf bound_ctrl:1
	v_exp_f32_e32 v18, v18
	v_exp_f32_e32 v19, v19
	v_exp_f32_e32 v20, v20
	v_exp_f32_e32 v21, v21
	v_add_f32_dpp v176, v176, v176 row_half_mirror row_mask:0xf bank_mask:0xf bound_ctrl:1
	v_add_f32_e32 v18, 1.0, v18
	v_add_f32_e32 v19, 1.0, v19
	v_add_f32_e32 v20, 1.0, v20
	v_add_f32_e32 v21, 1.0, v21
	v_add_f32_dpp v176, v176, v176 row_mirror row_mask:0xf bank_mask:0xf bound_ctrl:1
	v_rcp_f32_e32 v18, v18
	v_rcp_f32_e32 v19, v19
	v_rcp_f32_e32 v20, v20
	v_rcp_f32_e32 v21, v21
	v_sqrt_f32_e32 v176, v176
	v_add_f32_e32 v14, v190, v14
	v_add_f32_e32 v15, v191, v15
	v_add_f32_e32 v16, v192, v16
	v_add_f32_e32 v17, v193, v17
	v_max_f32_e32 v176, 0x2b8cbccc, v176
	v_mul_f32_e32 v14, 0xbfb8aa3b, v14
	v_mul_f32_e32 v15, 0xbfb8aa3b, v15
	v_mul_f32_e32 v16, 0xbfb8aa3b, v16
	v_mul_f32_e32 v17, 0xbfb8aa3b, v17
	v_rcp_f32_e32 v178, v176
	v_exp_f32_e32 v14, v14
	v_exp_f32_e32 v15, v15
	v_exp_f32_e32 v16, v16
	v_exp_f32_e32 v17, v17
	v_add_f32_e32 v14, 1.0, v14
	v_add_f32_e32 v15, 1.0, v15
	v_add_f32_e32 v16, 1.0, v16
	v_add_f32_e32 v17, 1.0, v17
	v_rcp_f32_e32 v14, v14
	v_rcp_f32_e32 v15, v15
	v_rcp_f32_e32 v16, v16
	v_rcp_f32_e32 v17, v17
	v_mul_f32_e32 v14, 0xbf1b4598, v14
	v_mul_f32_e32 v15, 0xbf1b4598, v15
	v_mul_f32_e32 v16, 0xbf1b4598, v16
	v_mul_f32_e32 v17, 0xbf1b4598, v17
	v_mul_f32_e32 v14, 0x3fb8aa3b, v14
	v_mul_f32_e32 v15, 0x3fb8aa3b, v15
	v_mul_f32_e32 v16, 0x3fb8aa3b, v16
	v_mul_f32_e32 v17, 0x3fb8aa3b, v17
	v_exp_f32_e32 v14, v14
	v_exp_f32_e32 v15, v15
	v_exp_f32_e32 v16, v16
	v_exp_f32_e32 v17, v17
	v_add_f32_e32 v152, -1.0, v18
	v_add_f32_e32 v153, -1.0, v19
	v_add_f32_e32 v154, -1.0, v20
	v_add_f32_e32 v155, -1.0, v21
	v_fma_f32 v152, v202, v152, 1.0
	v_fma_f32 v153, v203, v153, 1.0
	v_fma_f32 v154, v204, v154, 1.0
	v_fma_f32 v155, v205, v155, 1.0
	v_mul_f32_e32 v152, v136, v152
	v_mul_f32_e32 v153, v238, v153
	v_mul_f32_e32 v154, v137, v154
	v_mul_f32_e32 v155, v239, v155
	v_mul_f32_e32 v156, v134, v152
	v_mul_f32_e32 v157, v236, v153
	v_mul_f32_e32 v158, v135, v154
	v_mul_f32_e32 v159, v237, v155
	v_mul_f32_e32 v177, v206, v156
	v_fmac_f32_e32 v177, v207, v157
	v_fmac_f32_e32 v177, v208, v158
	v_fmac_f32_e32 v177, v209, v159
	v_mul_f32_e32 v148, v148, v178
	v_mul_f32_e32 v149, v149, v178
	v_add_f32_dpp v177, v177, v177 quad_perm:[1,0,3,2] row_mask:0xf bank_mask:0xf bound_ctrl:1
	v_mul_f32_e32 v150, v150, v178
	v_mul_f32_e32 v151, v151, v178
	v_add_f32_dpp v177, v177, v177 quad_perm:[2,3,0,1] row_mask:0xf bank_mask:0xf bound_ctrl:1
	v_mul_f32_e32 v18, v18, v148
	v_mul_f32_e32 v19, v19, v149
	v_add_f32_dpp v177, v177, v177 row_half_mirror row_mask:0xf bank_mask:0xf bound_ctrl:1
	v_mul_f32_e32 v20, v20, v150
	v_mul_f32_e32 v21, v21, v151
	v_add_f32_dpp v177, v177, v177 row_mirror row_mask:0xf bank_mask:0xf bound_ctrl:1
	s_lshl_b32 s0, s57, 9
	s_add_u32 s62, s34, s0
	s_addc_u32 s63, s35, 0
	v_mul_f32_e32 v156, v138, v177
	v_mul_f32_e32 v157, v240, v177
	v_mul_f32_e32 v158, v139, v177
	v_mul_f32_e32 v159, v241, v177
	v_cvt_pk_bf16_f32 v72, v134, v236
	v_cvt_pk_bf16_f32 v73, v135, v237
	global_store_dwordx2 v250, v[72:73], s[62:63]
	v_cvt_pk_bf16_f32 v74, v14, v15
	v_cvt_pk_bf16_f32 v75, v16, v17
	s_add_u32 s0, s62, 0x500000
	s_addc_u32 s1, s63, 0
	global_store_dwordx2 v250, v[74:75], s[0:1]
	v_cvt_pk_bf16_f32 v180, v152, v153
	v_cvt_pk_bf16_f32 v181, v154, v155
	s_add_u32 s0, s62, 0xa00000
	s_addc_u32 s1, s63, 0
	global_store_dwordx2 v250, v[180:181], s[0:1]
	v_cvt_pk_bf16_f32 v72, v138, v240
	v_cvt_pk_bf16_f32 v73, v139, v241
	s_add_u32 s0, s62, 0xf00000
	s_addc_u32 s1, s63, 0
	global_store_dwordx2 v250, v[72:73], s[0:1]
	v_cvt_pk_bf16_f32 v74, v148, v149
	v_cvt_pk_bf16_f32 v75, v150, v151
	s_add_u32 s0, s62, 0x1400000
	s_addc_u32 s1, s63, 0
	global_store_dwordx2 v250, v[74:75], s[0:1]
	v_cvt_pk_bf16_f32 v180, v18, v19
	v_cvt_pk_bf16_f32 v181, v20, v21
	s_add_u32 s0, s62, 0x1900000
	s_addc_u32 s1, s63, 0
	global_store_dwordx2 v250, v[180:181], s[0:1]
	v_cvt_pk_bf16_f32 v72, v156, v157
	v_cvt_pk_bf16_f32 v73, v158, v159
	s_lshl_b32 s0, s57, 9
	s_add_u32 s0, s42, s0
	s_addc_u32 s1, s43, 0
	global_store_dwordx2 v250, v[72:73], s[0:1]
	s_branch .LBB0_476
.Lprep_tok_d1:
	s_mul_i32 s0, s22, 2
	s_add_i32 s0, s0, 1
	s_lshl_b32 s1, s0, 10
	s_add_u32 s60, s60, s1
	s_addc_u32 s61, s61, 0
	s_add_u32 s62, s62, s1
	s_addc_u32 s63, s63, 0
	s_mul_i32 s1, s0, 0xc00
	s_add_u32 s58, s58, s1
	s_addc_u32 s59, s59, 0
	s_lshl_b32 s1, s22, 10
	s_add_u32 s64, s64, s1
	s_addc_u32 s65, s65, 0
	s_add_u32 s66, s66, s1
	s_addc_u32 s67, s67, 0
	s_add_u32 s68, s68, s1
	s_addc_u32 s69, s69, 0
	global_load_dwordx4 v[210:213], v251, s[58:59] offset:0
	global_load_dwordx4 v[214:217], v251, s[58:59] offset:1024
	global_load_dwordx4 v[218:221], v251, s[58:59] offset:2048
	global_load_dwordx4 v[198:201], v251, s[64:65] offset:0
	global_load_dwordx4 v[194:197], v251, s[62:63] offset:0
	global_load_dwordx4 v[190:193], v251, s[60:61] offset:0
	global_load_dwordx4 v[202:205], v251, s[66:67] offset:0
	global_load_dwordx4 v[206:209], v251, s[68:69] offset:0
	s_add_u32 s34, s34, 0x1e00000
	s_addc_u32 s35, s35, 0
	s_add_i32 s56, s53, 0
	s_cmpk_lt_i32 s56, 0x2000
	s_movk_i32 s0, 0x3ff
	s_cselect_b32 s0, 0xff, s0
	s_and_b32 s1, s56, s0
	s_cmp_lg_u32 s1, s0
	s_cselect_b32 s59, 1.0, 0
	s_cselect_b32 s1, 1, 0
	s_add_i32 s1, s56, s1
	s_mul_i32 s0, s56, 0x1d00
	s_add_u32 s76, s28, s0
	s_addc_u32 s77, s29, 0
	s_mul_i32 s0, s1, 0x1d00
	s_add_u32 s78, s28, s0
	s_addc_u32 s79, s29, 0
	global_load_dwordx2 v[222:223], v250, s[76:77] offset:0
	global_load_dwordx2 v[224:225], v250, s[76:77] offset:512
	global_load_dwordx2 v[226:227], v250, s[76:77] offset:1024
	global_load_dwordx2 v[228:229], v250, s[78:79] offset:0
	global_load_dwordx2 v[230:231], v250, s[78:79] offset:512
	global_load_dwordx2 v[232:233], v250, s[78:79] offset:1024
	s_lshl_b32 s0, s56, 9
	s_add_u32 s0, s42, s0
	s_addc_u32 s1, s43, 0
	global_load_dwordx2 v[234:235], v250, s[0:1]
	s_add_i32 s57, s53, 4
	s_cmpk_lt_i32 s57, 0x2000
	s_movk_i32 s0, 0x3ff
	s_cselect_b32 s0, 0xff, s0
	s_and_b32 s1, s57, s0
	s_cmp_lg_u32 s1, s0
	s_cselect_b32 s60, 1.0, 0
	s_cselect_b32 s1, 1, 0
	s_add_i32 s1, s57, s1
	s_mul_i32 s0, s57, 0x1d00
	s_add_u32 s80, s28, s0
	s_addc_u32 s81, s29, 0
	s_mul_i32 s0, s1, 0x1d00
	s_add_u32 s82, s28, s0
	s_addc_u32 s83, s29, 0
	global_load_dwordx2 v[236:237], v250, s[80:81] offset:0
	global_load_dwordx2 v[238:239], v250, s[80:81] offset:512
	global_load_dwordx2 v[240:241], v250, s[80:81] offset:1024
	global_load_dwordx2 v[242:243], v250, s[82:83] offset:0
	global_load_dwordx2 v[244:245], v250, s[82:83] offset:512
	global_load_dwordx2 v[246:247], v250, s[82:83] offset:1024
	s_lshl_b32 s0, s57, 9
	s_add_u32 s0, s42, s0
	s_addc_u32 s1, s43, 0
	global_load_dwordx2 v[248:249], v250, s[0:1]
	s_add_i32 s58, s53, 8
	s_cmpk_lt_i32 s58, 0x2000
	s_movk_i32 s0, 0x3ff
	s_cselect_b32 s0, 0xff, s0
	s_and_b32 s1, s58, s0
	s_cmp_lg_u32 s1, s0
	s_cselect_b32 s61, 1.0, 0
	s_cselect_b32 s1, 1, 0
	s_add_i32 s1, s58, s1
	s_mul_i32 s0, s58, 0x1d00
	s_add_u32 s84, s28, s0
	s_addc_u32 s85, s29, 0
	s_mul_i32 s0, s1, 0x1d00
	s_add_u32 s96, s28, s0
	s_addc_u32 s97, s29, 0
	global_load_dwordx2 v[0:1], v250, s[84:85] offset:0
	global_load_dwordx2 v[2:3], v250, s[84:85] offset:512
	global_load_dwordx2 v[4:5], v250, s[84:85] offset:1024
	global_load_dwordx2 v[6:7], v250, s[96:97] offset:0
	global_load_dwordx2 v[8:9], v250, s[96:97] offset:512
	global_load_dwordx2 v[10:11], v250, s[96:97] offset:1024
	s_lshl_b32 s0, s58, 9
	s_add_u32 s0, s42, s0
	s_addc_u32 s1, s43, 0
	global_load_dwordx2 v[12:13], v250, s[0:1]
	ds_read_b128 v[14:17], v31 offset:0
	ds_read_b128 v[18:21], v31 offset:20480
	ds_read_b128 v[22:25], v31 offset:4096
	ds_read_b128 v[26:29], v31 offset:24576
	s_waitcnt vmcnt(21)
	s_waitcnt vmcnt(14)
	v_lshlrev_b32_e32 v134, 16, v222
	v_and_b32_e32 v222, 0xffff0000, v222
	v_lshlrev_b32_e32 v135, 16, v223
	v_and_b32_e32 v223, 0xffff0000, v223
	v_lshlrev_b32_e32 v136, 16, v224
	v_and_b32_e32 v224, 0xffff0000, v224
	v_lshlrev_b32_e32 v137, 16, v225
	v_and_b32_e32 v225, 0xffff0000, v225
	v_lshlrev_b32_e32 v138, 16, v226
	v_and_b32_e32 v226, 0xffff0000, v226
	v_lshlrev_b32_e32 v139, 16, v227
	v_and_b32_e32 v227, 0xffff0000, v227
	v_lshlrev_b32_e32 v140, 16, v228
	v_and_b32_e32 v228, 0xffff0000, v228
	v_lshlrev_b32_e32 v141, 16, v229
	v_and_b32_e32 v229, 0xffff0000, v229
	v_lshlrev_b32_e32 v142, 16, v230
	v_and_b32_e32 v230, 0xffff0000, v230
	v_lshlrev_b32_e32 v143, 16, v231
	v_and_b32_e32 v231, 0xffff0000, v231
	v_lshlrev_b32_e32 v144, 16, v232
	v_and_b32_e32 v232, 0xffff0000, v232
	v_lshlrev_b32_e32 v145, 16, v233
	v_and_b32_e32 v233, 0xffff0000, v233
	v_lshlrev_b32_e32 v146, 16, v234
	v_and_b32_e32 v234, 0xffff0000, v234
	v_lshlrev_b32_e32 v147, 16, v235
	v_and_b32_e32 v235, 0xffff0000, v235
	v_fma_f32 v140, s59, v140, -v134
	v_fma_f32 v228, s59, v228, -v222
	v_fma_f32 v141, s59, v141, -v135
	v_fma_f32 v229, s59, v229, -v223
	v_fmac_f32_e32 v134, v210, v140
	v_fmac_f32_e32 v222, v211, v228
	v_fmac_f32_e32 v135, v212, v141
	v_fmac_f32_e32 v223, v213, v229
	v_fma_f32 v142, s59, v142, -v136
	v_fma_f32 v230, s59, v230, -v224
	v_fma_f32 v143, s59, v143, -v137
	v_fma_f32 v231, s59, v231, -v225
	v_fmac_f32_e32 v136, v214, v142
	v_fmac_f32_e32 v224, v215, v230
	v_fmac_f32_e32 v137, v216, v143
	v_fmac_f32_e32 v225, v217, v231
	v_fma_f32 v144, s59, v144, -v138
	v_fma_f32 v232, s59, v232, -v226
	v_fma_f32 v145, s59, v145, -v139
	v_fma_f32 v233, s59, v233, -v227
	v_fmac_f32_e32 v138, v218, v144
	v_fmac_f32_e32 v226, v219, v232
	v_fmac_f32_e32 v139, v220, v145
	v_fmac_f32_e32 v227, v221, v233
	v_mul_f32_e32 v148, v198, v136
	v_mul_f32_e32 v149, v199, v224
	v_mul_f32_e32 v150, v200, v137
	v_mul_f32_e32 v151, v201, v225
	v_mul_f32_e32 v176, v148, v148
	v_fmac_f32_e32 v176, v149, v149
	v_fmac_f32_e32 v176, v150, v150
	v_fmac_f32_e32 v176, v151, v151
	s_waitcnt lgkmcnt(2)
	v_add_f32_e32 v18, v194, v18
	v_add_f32_e32 v19, v195, v19
	v_add_f32_e32 v20, v196, v20
	v_add_f32_e32 v21, v197, v21
	v_add_f32_dpp v176, v176, v176 quad_perm:[1,0,3,2] row_mask:0xf bank_mask:0xf bound_ctrl:1
	v_mul_f32_e32 v18, 0xbfb8aa3b, v18
	v_mul_f32_e32 v19, 0xbfb8aa3b, v19
	v_mul_f32_e32 v20, 0xbfb8aa3b, v20
	v_mul_f32_e32 v21, 0xbfb8aa3b, v21
	v_add_f32_dpp v176, v176, v176 quad_perm:[2,3,0,1] row_mask:0xf bank_mask:0xf bound_ctrl:1
	v_exp_f32_e32 v18, v18
	v_exp_f32_e32 v19, v19
	v_exp_f32_e32 v20, v20
	v_exp_f32_e32 v21, v21
	v_add_f32_dpp v176, v176, v176 row_half_mirror row_mask:0xf bank_mask:0xf bound_ctrl:1
	v_add_f32_e32 v18, 1.0, v18
	v_add_f32_e32 v19, 1.0, v19
	v_add_f32_e32 v20, 1.0, v20
	v_add_f32_e32 v21, 1.0, v21
	v_add_f32_dpp v176, v176, v176 row_mirror row_mask:0xf bank_mask:0xf bound_ctrl:1
	v_rcp_f32_e32 v18, v18
	v_rcp_f32_e32 v19, v19
	v_rcp_f32_e32 v20, v20
	v_rcp_f32_e32 v21, v21
	v_sqrt_f32_e32 v176, v176
	v_add_f32_e32 v14, v190, v14
	v_add_f32_e32 v15, v191, v15
	v_add_f32_e32 v16, v192, v16
	v_add_f32_e32 v17, v193, v17
	v_max_f32_e32 v176, 0x2b8cbccc, v176
	v_mul_f32_e32 v14, 0xbfb8aa3b, v14
	v_mul_f32_e32 v15, 0xbfb8aa3b, v15
	v_mul_f32_e32 v16, 0xbfb8aa3b, v16
	v_mul_f32_e32 v17, 0xbfb8aa3b, v17
	v_rcp_f32_e32 v178, v176
	v_exp_f32_e32 v14, v14
	v_exp_f32_e32 v15, v15
	v_exp_f32_e32 v16, v16
	v_exp_f32_e32 v17, v17
	v_add_f32_e32 v14, 1.0, v14
	v_add_f32_e32 v15, 1.0, v15
	v_add_f32_e32 v16, 1.0, v16
	v_add_f32_e32 v17, 1.0, v17
	v_rcp_f32_e32 v14, v14
	v_rcp_f32_e32 v15, v15
	v_rcp_f32_e32 v16, v16
	v_rcp_f32_e32 v17, v17
	v_mul_f32_e32 v14, 0xbf1b4598, v14
	v_mul_f32_e32 v15, 0xbf1b4598, v15
	v_mul_f32_e32 v16, 0xbf1b4598, v16
	v_mul_f32_e32 v17, 0xbf1b4598, v17
	v_mul_f32_e32 v14, 0x3fb8aa3b, v14
	v_mul_f32_e32 v15, 0x3fb8aa3b, v15
	v_mul_f32_e32 v16, 0x3fb8aa3b, v16
	v_mul_f32_e32 v17, 0x3fb8aa3b, v17
	v_exp_f32_e32 v14, v14
	v_exp_f32_e32 v15, v15
	v_exp_f32_e32 v16, v16
	v_exp_f32_e32 v17, v17
	v_add_f32_e32 v152, -1.0, v18
	v_add_f32_e32 v153, -1.0, v19
	v_add_f32_e32 v154, -1.0, v20
	v_add_f32_e32 v155, -1.0, v21
	v_fma_f32 v152, v202, v152, 1.0
	v_fma_f32 v153, v203, v153, 1.0
	v_fma_f32 v154, v204, v154, 1.0
	v_fma_f32 v155, v205, v155, 1.0
	v_mul_f32_e32 v152, v136, v152
	v_mul_f32_e32 v153, v224, v153
	v_mul_f32_e32 v154, v137, v154
	v_mul_f32_e32 v155, v225, v155
	v_mul_f32_e32 v156, v134, v152
	v_mul_f32_e32 v157, v222, v153
	v_mul_f32_e32 v158, v135, v154
	v_mul_f32_e32 v159, v223, v155
	v_mul_f32_e32 v177, v206, v156
	v_fmac_f32_e32 v177, v207, v157
	v_fmac_f32_e32 v177, v208, v158
	v_fmac_f32_e32 v177, v209, v159
	v_mul_f32_e32 v148, v148, v178
	v_mul_f32_e32 v149, v149, v178
	v_add_f32_dpp v177, v177, v177 quad_perm:[1,0,3,2] row_mask:0xf bank_mask:0xf bound_ctrl:1
	v_mul_f32_e32 v150, v150, v178
	v_mul_f32_e32 v151, v151, v178
	v_add_f32_dpp v177, v177, v177 quad_perm:[2,3,0,1] row_mask:0xf bank_mask:0xf bound_ctrl:1
	v_mul_f32_e32 v18, v18, v148
	v_mul_f32_e32 v19, v19, v149
	v_add_f32_dpp v177, v177, v177 row_half_mirror row_mask:0xf bank_mask:0xf bound_ctrl:1
	v_mul_f32_e32 v20, v20, v150
	v_mul_f32_e32 v21, v21, v151
	v_add_f32_dpp v177, v177, v177 row_mirror row_mask:0xf bank_mask:0xf bound_ctrl:1
	s_lshl_b32 s0, s56, 9
	s_add_u32 s62, s34, s0
	s_addc_u32 s63, s35, 0
	v_fmac_f32_e32 v146, v138, v177
	v_fmac_f32_e32 v234, v226, v177
	v_fmac_f32_e32 v147, v139, v177
	v_fmac_f32_e32 v235, v227, v177
	v_cvt_pk_bf16_f32 v72, v134, v222
	v_cvt_pk_bf16_f32 v73, v135, v223
	global_store_dwordx2 v250, v[72:73], s[62:63]
	v_cvt_pk_bf16_f32 v74, v14, v15
	v_cvt_pk_bf16_f32 v75, v16, v17
	s_add_u32 s0, s62, 0x500000
	s_addc_u32 s1, s63, 0
	global_store_dwordx2 v250, v[74:75], s[0:1]
	v_cvt_pk_bf16_f32 v180, v152, v153
	v_cvt_pk_bf16_f32 v181, v154, v155
	s_add_u32 s0, s62, 0xa00000
	s_addc_u32 s1, s63, 0
	global_store_dwordx2 v250, v[180:181], s[0:1]
	v_cvt_pk_bf16_f32 v72, v138, v226
	v_cvt_pk_bf16_f32 v73, v139, v227
	s_add_u32 s0, s62, 0xf00000
	s_addc_u32 s1, s63, 0
	global_store_dwordx2 v250, v[72:73], s[0:1]
	v_cvt_pk_bf16_f32 v74, v148, v149
	v_cvt_pk_bf16_f32 v75, v150, v151
	s_add_u32 s0, s62, 0x1400000
	s_addc_u32 s1, s63, 0
	global_store_dwordx2 v250, v[74:75], s[0:1]
	v_cvt_pk_bf16_f32 v180, v18, v19
	v_cvt_pk_bf16_f32 v181, v20, v21
	s_add_u32 s0, s62, 0x1900000
	s_addc_u32 s1, s63, 0
	global_store_dwordx2 v250, v[180:181], s[0:1]
	v_cvt_pk_bf16_f32 v72, v146, v234
	v_cvt_pk_bf16_f32 v73, v147, v235
	s_lshl_b32 s0, s56, 9
	s_add_u32 s0, s42, s0
	s_addc_u32 s1, s43, 0
	global_store_dwordx2 v250, v[72:73], s[0:1]
	s_add_i32 s56, s53, 12
	s_cmpk_lt_i32 s56, 0x2000
	s_movk_i32 s0, 0x3ff
	s_cselect_b32 s0, 0xff, s0
	s_and_b32 s1, s56, s0
	s_cmp_lg_u32 s1, s0
	s_cselect_b32 s59, 1.0, 0
	s_cselect_b32 s1, 1, 0
	s_add_i32 s1, s56, s1
	s_mul_i32 s0, s56, 0x1d00
	s_add_u32 s76, s28, s0
	s_addc_u32 s77, s29, 0
	s_mul_i32 s0, s1, 0x1d00
	s_add_u32 s78, s28, s0
	s_addc_u32 s79, s29, 0
	global_load_dwordx2 v[222:223], v250, s[76:77] offset:0
	global_load_dwordx2 v[224:225], v250, s[76:77] offset:512
	global_load_dwordx2 v[226:227], v250, s[76:77] offset:1024
	global_load_dwordx2 v[228:229], v250, s[78:79] offset:0
	global_load_dwordx2 v[230:231], v250, s[78:79] offset:512
	global_load_dwordx2 v[232:233], v250, s[78:79] offset:1024
	s_lshl_b32 s0, s56, 9
	s_add_u32 s0, s42, s0
	s_addc_u32 s1, s43, 0
	global_load_dwordx2 v[234:235], v250, s[0:1]
	ds_read_b128 v[14:17], v31 offset:8192
	ds_read_b128 v[18:21], v31 offset:28672
	s_waitcnt vmcnt(21)
	v_lshlrev_b32_e32 v134, 16, v236
	v_and_b32_e32 v236, 0xffff0000, v236
	v_lshlrev_b32_e32 v135, 16, v237
	v_and_b32_e32 v237, 0xffff0000, v237
	v_lshlrev_b32_e32 v136, 16, v238
	v_and_b32_e32 v238, 0xffff0000, v238
	v_lshlrev_b32_e32 v137, 16, v239
	v_and_b32_e32 v239, 0xffff0000, v239
	v_lshlrev_b32_e32 v138, 16, v240
	v_and_b32_e32 v240, 0xffff0000, v240
	v_lshlrev_b32_e32 v139, 16, v241
	v_and_b32_e32 v241, 0xffff0000, v241
	v_lshlrev_b32_e32 v140, 16, v242
	v_and_b32_e32 v242, 0xffff0000, v242
	v_lshlrev_b32_e32 v141, 16, v243
	v_and_b32_e32 v243, 0xffff0000, v243
	v_lshlrev_b32_e32 v142, 16, v244
	v_and_b32_e32 v244, 0xffff0000, v244
	v_lshlrev_b32_e32 v143, 16, v245
	v_and_b32_e32 v245, 0xffff0000, v245
	v_lshlrev_b32_e32 v144, 16, v246
	v_and_b32_e32 v246, 0xffff0000, v246
	v_lshlrev_b32_e32 v145, 16, v247
	v_and_b32_e32 v247, 0xffff0000, v247
	v_lshlrev_b32_e32 v146, 16, v248
	v_and_b32_e32 v248, 0xffff0000, v248
	v_lshlrev_b32_e32 v147, 16, v249
	v_and_b32_e32 v249, 0xffff0000, v249
	v_fma_f32 v140, s60, v140, -v134
	v_fma_f32 v242, s60, v242, -v236
	v_fma_f32 v141, s60, v141, -v135
	v_fma_f32 v243, s60, v243, -v237
	v_fmac_f32_e32 v134, v210, v140
	v_fmac_f32_e32 v236, v211, v242
	v_fmac_f32_e32 v135, v212, v141
	v_fmac_f32_e32 v237, v213, v243
	v_fma_f32 v142, s60, v142, -v136
	v_fma_f32 v244, s60, v244, -v238
	v_fma_f32 v143, s60, v143, -v137
	v_fma_f32 v245, s60, v245, -v239
	v_fmac_f32_e32 v136, v214, v142
	v_fmac_f32_e32 v238, v215, v244
	v_fmac_f32_e32 v137, v216, v143
	v_fmac_f32_e32 v239, v217, v245
	v_fma_f32 v144, s60, v144, -v138
	v_fma_f32 v246, s60, v246, -v240
	v_fma_f32 v145, s60, v145, -v139
	v_fma_f32 v247, s60, v247, -v241
	v_fmac_f32_e32 v138, v218, v144
	v_fmac_f32_e32 v240, v219, v246
	v_fmac_f32_e32 v139, v220, v145
	v_fmac_f32_e32 v241, v221, v247
	v_mul_f32_e32 v148, v198, v136
	v_mul_f32_e32 v149, v199, v238
	v_mul_f32_e32 v150, v200, v137
	v_mul_f32_e32 v151, v201, v239
	v_mul_f32_e32 v176, v148, v148
	v_fmac_f32_e32 v176, v149, v149
	v_fmac_f32_e32 v176, v150, v150
	v_fmac_f32_e32 v176, v151, v151
	s_waitcnt lgkmcnt(2)
	v_add_f32_e32 v26, v194, v26
	v_add_f32_e32 v27, v195, v27
	v_add_f32_e32 v28, v196, v28
	v_add_f32_e32 v29, v197, v29
	v_add_f32_dpp v176, v176, v176 quad_perm:[1,0,3,2] row_mask:0xf bank_mask:0xf bound_ctrl:1
	v_mul_f32_e32 v26, 0xbfb8aa3b, v26
	v_mul_f32_e32 v27, 0xbfb8aa3b, v27
	v_mul_f32_e32 v28, 0xbfb8aa3b, v28
	v_mul_f32_e32 v29, 0xbfb8aa3b, v29
	v_add_f32_dpp v176, v176, v176 quad_perm:[2,3,0,1] row_mask:0xf bank_mask:0xf bound_ctrl:1
	v_exp_f32_e32 v26, v26
	v_exp_f32_e32 v27, v27
	v_exp_f32_e32 v28, v28
	v_exp_f32_e32 v29, v29
	v_add_f32_dpp v176, v176, v176 row_half_mirror row_mask:0xf bank_mask:0xf bound_ctrl:1
	v_add_f32_e32 v26, 1.0, v26
	v_add_f32_e32 v27, 1.0, v27
	v_add_f32_e32 v28, 1.0, v28
	v_add_f32_e32 v29, 1.0, v29
	v_add_f32_dpp v176, v176, v176 row_mirror row_mask:0xf bank_mask:0xf bound_ctrl:1
	v_rcp_f32_e32 v26, v26
	v_rcp_f32_e32 v27, v27
	v_rcp_f32_e32 v28, v28
	v_rcp_f32_e32 v29, v29
	v_sqrt_f32_e32 v176, v176
	v_add_f32_e32 v22, v190, v22
	v_add_f32_e32 v23, v191, v23
	v_add_f32_e32 v24, v192, v24
	v_add_f32_e32 v25, v193, v25
	v_max_f32_e32 v176, 0x2b8cbccc, v176
	v_mul_f32_e32 v22, 0xbfb8aa3b, v22
	v_mul_f32_e32 v23, 0xbfb8aa3b, v23
	v_mul_f32_e32 v24, 0xbfb8aa3b, v24
	v_mul_f32_e32 v25, 0xbfb8aa3b, v25
	v_rcp_f32_e32 v178, v176
	v_exp_f32_e32 v22, v22
	v_exp_f32_e32 v23, v23
	v_exp_f32_e32 v24, v24
	v_exp_f32_e32 v25, v25
	v_add_f32_e32 v22, 1.0, v22
	v_add_f32_e32 v23, 1.0, v23
	v_add_f32_e32 v24, 1.0, v24
	v_add_f32_e32 v25, 1.0, v25
	v_rcp_f32_e32 v22, v22
	v_rcp_f32_e32 v23, v23
	v_rcp_f32_e32 v24, v24
	v_rcp_f32_e32 v25, v25
	v_mul_f32_e32 v22, 0xbf1b4598, v22
	v_mul_f32_e32 v23, 0xbf1b4598, v23
	v_mul_f32_e32 v24, 0xbf1b4598, v24
	v_mul_f32_e32 v25, 0xbf1b4598, v25
	v_mul_f32_e32 v22, 0x3fb8aa3b, v22
	v_mul_f32_e32 v23, 0x3fb8aa3b, v23
	v_mul_f32_e32 v24, 0x3fb8aa3b, v24
	v_mul_f32_e32 v25, 0x3fb8aa3b, v25
	v_exp_f32_e32 v22, v22
	v_exp_f32_e32 v23, v23
	v_exp_f32_e32 v24, v24
	v_exp_f32_e32 v25, v25
	v_add_f32_e32 v152, -1.0, v26
	v_add_f32_e32 v153, -1.0, v27
	v_add_f32_e32 v154, -1.0, v28
	v_add_f32_e32 v155, -1.0, v29
	v_fma_f32 v152, v202, v152, 1.0
	v_fma_f32 v153, v203, v153, 1.0
	v_fma_f32 v154, v204, v154, 1.0
	v_fma_f32 v155, v205, v155, 1.0
	v_mul_f32_e32 v152, v136, v152
	v_mul_f32_e32 v153, v238, v153
	v_mul_f32_e32 v154, v137, v154
	v_mul_f32_e32 v155, v239, v155
	v_mul_f32_e32 v156, v134, v152
	v_mul_f32_e32 v157, v236, v153
	v_mul_f32_e32 v158, v135, v154
	v_mul_f32_e32 v159, v237, v155
	v_mul_f32_e32 v177, v206, v156
	v_fmac_f32_e32 v177, v207, v157
	v_fmac_f32_e32 v177, v208, v158
	v_fmac_f32_e32 v177, v209, v159
	v_mul_f32_e32 v148, v148, v178
	v_mul_f32_e32 v149, v149, v178
	v_add_f32_dpp v177, v177, v177 quad_perm:[1,0,3,2] row_mask:0xf bank_mask:0xf bound_ctrl:1
	v_mul_f32_e32 v150, v150, v178
	v_mul_f32_e32 v151, v151, v178
	v_add_f32_dpp v177, v177, v177 quad_perm:[2,3,0,1] row_mask:0xf bank_mask:0xf bound_ctrl:1
	v_mul_f32_e32 v26, v26, v148
	v_mul_f32_e32 v27, v27, v149
	v_add_f32_dpp v177, v177, v177 row_half_mirror row_mask:0xf bank_mask:0xf bound_ctrl:1
	v_mul_f32_e32 v28, v28, v150
	v_mul_f32_e32 v29, v29, v151
	v_add_f32_dpp v177, v177, v177 row_mirror row_mask:0xf bank_mask:0xf bound_ctrl:1
	s_lshl_b32 s0, s57, 9
	s_add_u32 s62, s34, s0
	s_addc_u32 s63, s35, 0
	v_fmac_f32_e32 v146, v138, v177
	v_fmac_f32_e32 v248, v240, v177
	v_fmac_f32_e32 v147, v139, v177
	v_fmac_f32_e32 v249, v241, v177
	v_cvt_pk_bf16_f32 v72, v134, v236
	v_cvt_pk_bf16_f32 v73, v135, v237
	global_store_dwordx2 v250, v[72:73], s[62:63]
	v_cvt_pk_bf16_f32 v74, v22, v23
	v_cvt_pk_bf16_f32 v75, v24, v25
	s_add_u32 s0, s62, 0x500000
	s_addc_u32 s1, s63, 0
	global_store_dwordx2 v250, v[74:75], s[0:1]
	v_cvt_pk_bf16_f32 v180, v152, v153
	v_cvt_pk_bf16_f32 v181, v154, v155
	s_add_u32 s0, s62, 0xa00000
	s_addc_u32 s1, s63, 0
	global_store_dwordx2 v250, v[180:181], s[0:1]
	v_cvt_pk_bf16_f32 v72, v138, v240
	v_cvt_pk_bf16_f32 v73, v139, v241
	s_add_u32 s0, s62, 0xf00000
	s_addc_u32 s1, s63, 0
	global_store_dwordx2 v250, v[72:73], s[0:1]
	v_cvt_pk_bf16_f32 v74, v148, v149
	v_cvt_pk_bf16_f32 v75, v150, v151
	s_add_u32 s0, s62, 0x1400000
	s_addc_u32 s1, s63, 0
	global_store_dwordx2 v250, v[74:75], s[0:1]
	v_cvt_pk_bf16_f32 v180, v26, v27
	v_cvt_pk_bf16_f32 v181, v28, v29
	s_add_u32 s0, s62, 0x1900000
	s_addc_u32 s1, s63, 0
	global_store_dwordx2 v250, v[180:181], s[0:1]
	v_cvt_pk_bf16_f32 v72, v146, v248
	v_cvt_pk_bf16_f32 v73, v147, v249
	s_lshl_b32 s0, s57, 9
	s_add_u32 s0, s42, s0
	s_addc_u32 s1, s43, 0
	global_store_dwordx2 v250, v[72:73], s[0:1]
	s_add_i32 s57, s53, 16
	s_cmpk_lt_i32 s57, 0x2000
	s_movk_i32 s0, 0x3ff
	s_cselect_b32 s0, 0xff, s0
	s_and_b32 s1, s57, s0
	s_cmp_lg_u32 s1, s0
	s_cselect_b32 s60, 1.0, 0
	s_cselect_b32 s1, 1, 0
	s_add_i32 s1, s57, s1
	s_mul_i32 s0, s57, 0x1d00
	s_add_u32 s80, s28, s0
	s_addc_u32 s81, s29, 0
	s_mul_i32 s0, s1, 0x1d00
	s_add_u32 s82, s28, s0
	s_addc_u32 s83, s29, 0
	global_load_dwordx2 v[236:237], v250, s[80:81] offset:0
	global_load_dwordx2 v[238:239], v250, s[80:81] offset:512
	global_load_dwordx2 v[240:241], v250, s[80:81] offset:1024
	global_load_dwordx2 v[242:243], v250, s[82:83] offset:0
	global_load_dwordx2 v[244:245], v250, s[82:83] offset:512
	global_load_dwordx2 v[246:247], v250, s[82:83] offset:1024
	s_lshl_b32 s0, s57, 9
	s_add_u32 s0, s42, s0
	s_addc_u32 s1, s43, 0
	global_load_dwordx2 v[248:249], v250, s[0:1]
	ds_read_b128 v[22:25], v31 offset:12288
	ds_read_b128 v[26:29], v31 offset:32768
	s_waitcnt vmcnt(28)
	v_lshlrev_b32_e32 v134, 16, v0
	v_and_b32_e32 v0, 0xffff0000, v0
	v_lshlrev_b32_e32 v135, 16, v1
	v_and_b32_e32 v1, 0xffff0000, v1
	v_lshlrev_b32_e32 v136, 16, v2
	v_and_b32_e32 v2, 0xffff0000, v2
	v_lshlrev_b32_e32 v137, 16, v3
	v_and_b32_e32 v3, 0xffff0000, v3
	v_lshlrev_b32_e32 v138, 16, v4
	v_and_b32_e32 v4, 0xffff0000, v4
	v_lshlrev_b32_e32 v139, 16, v5
	v_and_b32_e32 v5, 0xffff0000, v5
	v_lshlrev_b32_e32 v140, 16, v6
	v_and_b32_e32 v6, 0xffff0000, v6
	v_lshlrev_b32_e32 v141, 16, v7
	v_and_b32_e32 v7, 0xffff0000, v7
	v_lshlrev_b32_e32 v142, 16, v8
	v_and_b32_e32 v8, 0xffff0000, v8
	v_lshlrev_b32_e32 v143, 16, v9
	v_and_b32_e32 v9, 0xffff0000, v9
	v_lshlrev_b32_e32 v144, 16, v10
	v_and_b32_e32 v10, 0xffff0000, v10
	v_lshlrev_b32_e32 v145, 16, v11
	v_and_b32_e32 v11, 0xffff0000, v11
	v_lshlrev_b32_e32 v146, 16, v12
	v_and_b32_e32 v12, 0xffff0000, v12
	v_lshlrev_b32_e32 v147, 16, v13
	v_and_b32_e32 v13, 0xffff0000, v13
	v_fma_f32 v140, s61, v140, -v134
	v_fma_f32 v6, s61, v6, -v0
	v_fma_f32 v141, s61, v141, -v135
	v_fma_f32 v7, s61, v7, -v1
	v_fmac_f32_e32 v134, v210, v140
	v_fmac_f32_e32 v0, v211, v6
	v_fmac_f32_e32 v135, v212, v141
	v_fmac_f32_e32 v1, v213, v7
	v_fma_f32 v142, s61, v142, -v136
	v_fma_f32 v8, s61, v8, -v2
	v_fma_f32 v143, s61, v143, -v137
	v_fma_f32 v9, s61, v9, -v3
	v_fmac_f32_e32 v136, v214, v142
	v_fmac_f32_e32 v2, v215, v8
	v_fmac_f32_e32 v137, v216, v143
	v_fmac_f32_e32 v3, v217, v9
	v_fma_f32 v144, s61, v144, -v138
	v_fma_f32 v10, s61, v10, -v4
	v_fma_f32 v145, s61, v145, -v139
	v_fma_f32 v11, s61, v11, -v5
	v_fmac_f32_e32 v138, v218, v144
	v_fmac_f32_e32 v4, v219, v10
	v_fmac_f32_e32 v139, v220, v145
	v_fmac_f32_e32 v5, v221, v11
	v_mul_f32_e32 v148, v198, v136
	v_mul_f32_e32 v149, v199, v2
	v_mul_f32_e32 v150, v200, v137
	v_mul_f32_e32 v151, v201, v3
	v_mul_f32_e32 v176, v148, v148
	v_fmac_f32_e32 v176, v149, v149
	v_fmac_f32_e32 v176, v150, v150
	v_fmac_f32_e32 v176, v151, v151
	s_waitcnt lgkmcnt(2)
	v_add_f32_e32 v18, v194, v18
	v_add_f32_e32 v19, v195, v19
	v_add_f32_e32 v20, v196, v20
	v_add_f32_e32 v21, v197, v21
	v_add_f32_dpp v176, v176, v176 quad_perm:[1,0,3,2] row_mask:0xf bank_mask:0xf bound_ctrl:1
	v_mul_f32_e32 v18, 0xbfb8aa3b, v18
	v_mul_f32_e32 v19, 0xbfb8aa3b, v19
	v_mul_f32_e32 v20, 0xbfb8aa3b, v20
	v_mul_f32_e32 v21, 0xbfb8aa3b, v21
	v_add_f32_dpp v176, v176, v176 quad_perm:[2,3,0,1] row_mask:0xf bank_mask:0xf bound_ctrl:1
	v_exp_f32_e32 v18, v18
	v_exp_f32_e32 v19, v19
	v_exp_f32_e32 v20, v20
	v_exp_f32_e32 v21, v21
	v_add_f32_dpp v176, v176, v176 row_half_mirror row_mask:0xf bank_mask:0xf bound_ctrl:1
	v_add_f32_e32 v18, 1.0, v18
	v_add_f32_e32 v19, 1.0, v19
	v_add_f32_e32 v20, 1.0, v20
	v_add_f32_e32 v21, 1.0, v21
	v_add_f32_dpp v176, v176, v176 row_mirror row_mask:0xf bank_mask:0xf bound_ctrl:1
	v_rcp_f32_e32 v18, v18
	v_rcp_f32_e32 v19, v19
	v_rcp_f32_e32 v20, v20
	v_rcp_f32_e32 v21, v21
	v_sqrt_f32_e32 v176, v176
	v_add_f32_e32 v14, v190, v14
	v_add_f32_e32 v15, v191, v15
	v_add_f32_e32 v16, v192, v16
	v_add_f32_e32 v17, v193, v17
	v_max_f32_e32 v176, 0x2b8cbccc, v176
	v_mul_f32_e32 v14, 0xbfb8aa3b, v14
	v_mul_f32_e32 v15, 0xbfb8aa3b, v15
	v_mul_f32_e32 v16, 0xbfb8aa3b, v16
	v_mul_f32_e32 v17, 0xbfb8aa3b, v17
	v_rcp_f32_e32 v178, v176
	v_exp_f32_e32 v14, v14
	v_exp_f32_e32 v15, v15
	v_exp_f32_e32 v16, v16
	v_exp_f32_e32 v17, v17
	v_add_f32_e32 v14, 1.0, v14
	v_add_f32_e32 v15, 1.0, v15
	v_add_f32_e32 v16, 1.0, v16
	v_add_f32_e32 v17, 1.0, v17
	v_rcp_f32_e32 v14, v14
	v_rcp_f32_e32 v15, v15
	v_rcp_f32_e32 v16, v16
	v_rcp_f32_e32 v17, v17
	v_mul_f32_e32 v14, 0xbf1b4598, v14
	v_mul_f32_e32 v15, 0xbf1b4598, v15
	v_mul_f32_e32 v16, 0xbf1b4598, v16
	v_mul_f32_e32 v17, 0xbf1b4598, v17
	v_mul_f32_e32 v14, 0x3fb8aa3b, v14
	v_mul_f32_e32 v15, 0x3fb8aa3b, v15
	v_mul_f32_e32 v16, 0x3fb8aa3b, v16
	v_mul_f32_e32 v17, 0x3fb8aa3b, v17
	v_exp_f32_e32 v14, v14
	v_exp_f32_e32 v15, v15
	v_exp_f32_e32 v16, v16
	v_exp_f32_e32 v17, v17
	v_add_f32_e32 v152, -1.0, v18
	v_add_f32_e32 v153, -1.0, v19
	v_add_f32_e32 v154, -1.0, v20
	v_add_f32_e32 v155, -1.0, v21
	v_fma_f32 v152, v202, v152, 1.0
	v_fma_f32 v153, v203, v153, 1.0
	v_fma_f32 v154, v204, v154, 1.0
	v_fma_f32 v155, v205, v155, 1.0
	v_mul_f32_e32 v152, v136, v152
	v_mul_f32_e32 v153, v2, v153
	v_mul_f32_e32 v154, v137, v154
	v_mul_f32_e32 v155, v3, v155
	v_mul_f32_e32 v156, v134, v152
	v_mul_f32_e32 v157, v0, v153
	v_mul_f32_e32 v158, v135, v154
	v_mul_f32_e32 v159, v1, v155
	v_mul_f32_e32 v177, v206, v156
	v_fmac_f32_e32 v177, v207, v157
	v_fmac_f32_e32 v177, v208, v158
	v_fmac_f32_e32 v177, v209, v159
	v_mul_f32_e32 v148, v148, v178
	v_mul_f32_e32 v149, v149, v178
	v_add_f32_dpp v177, v177, v177 quad_perm:[1,0,3,2] row_mask:0xf bank_mask:0xf bound_ctrl:1
	v_mul_f32_e32 v150, v150, v178
	v_mul_f32_e32 v151, v151, v178
	v_add_f32_dpp v177, v177, v177 quad_perm:[2,3,0,1] row_mask:0xf bank_mask:0xf bound_ctrl:1
	v_mul_f32_e32 v18, v18, v148
	v_mul_f32_e32 v19, v19, v149
	v_add_f32_dpp v177, v177, v177 row_half_mirror row_mask:0xf bank_mask:0xf bound_ctrl:1
	v_mul_f32_e32 v20, v20, v150
	v_mul_f32_e32 v21, v21, v151
	v_add_f32_dpp v177, v177, v177 row_mirror row_mask:0xf bank_mask:0xf bound_ctrl:1
	s_lshl_b32 s0, s58, 9
	s_add_u32 s62, s34, s0
	s_addc_u32 s63, s35, 0
	v_fmac_f32_e32 v146, v138, v177
	v_fmac_f32_e32 v12, v4, v177
	v_fmac_f32_e32 v147, v139, v177
	v_fmac_f32_e32 v13, v5, v177
	v_cvt_pk_bf16_f32 v72, v134, v0
	v_cvt_pk_bf16_f32 v73, v135, v1
	global_store_dwordx2 v250, v[72:73], s[62:63]
	v_cvt_pk_bf16_f32 v74, v14, v15
	v_cvt_pk_bf16_f32 v75, v16, v17
	s_add_u32 s0, s62, 0x500000
	s_addc_u32 s1, s63, 0
	global_store_dwordx2 v250, v[74:75], s[0:1]
	v_cvt_pk_bf16_f32 v180, v152, v153
	v_cvt_pk_bf16_f32 v181, v154, v155
	s_add_u32 s0, s62, 0xa00000
	s_addc_u32 s1, s63, 0
	global_store_dwordx2 v250, v[180:181], s[0:1]
	v_cvt_pk_bf16_f32 v72, v138, v4
	v_cvt_pk_bf16_f32 v73, v139, v5
	s_add_u32 s0, s62, 0xf00000
	s_addc_u32 s1, s63, 0
	global_store_dwordx2 v250, v[72:73], s[0:1]
	v_cvt_pk_bf16_f32 v74, v148, v149
	v_cvt_pk_bf16_f32 v75, v150, v151
	s_add_u32 s0, s62, 0x1400000
	s_addc_u32 s1, s63, 0
	global_store_dwordx2 v250, v[74:75], s[0:1]
	v_cvt_pk_bf16_f32 v180, v18, v19
	v_cvt_pk_bf16_f32 v181, v20, v21
	s_add_u32 s0, s62, 0x1900000
	s_addc_u32 s1, s63, 0
	global_store_dwordx2 v250, v[180:181], s[0:1]
	v_cvt_pk_bf16_f32 v72, v146, v12
	v_cvt_pk_bf16_f32 v73, v147, v13
	s_lshl_b32 s0, s58, 9
	s_add_u32 s0, s42, s0
	s_addc_u32 s1, s43, 0
	global_store_dwordx2 v250, v[72:73], s[0:1]
	ds_read_b128 v[14:17], v31 offset:16384
	ds_read_b128 v[18:21], v31 offset:36864
	s_waitcnt vmcnt(21)
	v_lshlrev_b32_e32 v134, 16, v222
	v_and_b32_e32 v222, 0xffff0000, v222
	v_lshlrev_b32_e32 v135, 16, v223
	v_and_b32_e32 v223, 0xffff0000, v223
	v_lshlrev_b32_e32 v136, 16, v224
	v_and_b32_e32 v224, 0xffff0000, v224
	v_lshlrev_b32_e32 v137, 16, v225
	v_and_b32_e32 v225, 0xffff0000, v225
	v_lshlrev_b32_e32 v138, 16, v226
	v_and_b32_e32 v226, 0xffff0000, v226
	v_lshlrev_b32_e32 v139, 16, v227
	v_and_b32_e32 v227, 0xffff0000, v227
	v_lshlrev_b32_e32 v140, 16, v228
	v_and_b32_e32 v228, 0xffff0000, v228
	v_lshlrev_b32_e32 v141, 16, v229
	v_and_b32_e32 v229, 0xffff0000, v229
	v_lshlrev_b32_e32 v142, 16, v230
	v_and_b32_e32 v230, 0xffff0000, v230
	v_lshlrev_b32_e32 v143, 16, v231
	v_and_b32_e32 v231, 0xffff0000, v231
	v_lshlrev_b32_e32 v144, 16, v232
	v_and_b32_e32 v232, 0xffff0000, v232
	v_lshlrev_b32_e32 v145, 16, v233
	v_and_b32_e32 v233, 0xffff0000, v233
	v_lshlrev_b32_e32 v146, 16, v234
	v_and_b32_e32 v234, 0xffff0000, v234
	v_lshlrev_b32_e32 v147, 16, v235
	v_and_b32_e32 v235, 0xffff0000, v235
	v_fma_f32 v140, s59, v140, -v134
	v_fma_f32 v228, s59, v228, -v222
	v_fma_f32 v141, s59, v141, -v135
	v_fma_f32 v229, s59, v229, -v223
	v_fmac_f32_e32 v134, v210, v140
	v_fmac_f32_e32 v222, v211, v228
	v_fmac_f32_e32 v135, v212, v141
	v_fmac_f32_e32 v223, v213, v229
	v_fma_f32 v142, s59, v142, -v136
	v_fma_f32 v230, s59, v230, -v224
	v_fma_f32 v143, s59, v143, -v137
	v_fma_f32 v231, s59, v231, -v225
	v_fmac_f32_e32 v136, v214, v142
	v_fmac_f32_e32 v224, v215, v230
	v_fmac_f32_e32 v137, v216, v143
	v_fmac_f32_e32 v225, v217, v231
	v_fma_f32 v144, s59, v144, -v138
	v_fma_f32 v232, s59, v232, -v226
	v_fma_f32 v145, s59, v145, -v139
	v_fma_f32 v233, s59, v233, -v227
	v_fmac_f32_e32 v138, v218, v144
	v_fmac_f32_e32 v226, v219, v232
	v_fmac_f32_e32 v139, v220, v145
	v_fmac_f32_e32 v227, v221, v233
	v_mul_f32_e32 v148, v198, v136
	v_mul_f32_e32 v149, v199, v224
	v_mul_f32_e32 v150, v200, v137
	v_mul_f32_e32 v151, v201, v225
	v_mul_f32_e32 v176, v148, v148
	v_fmac_f32_e32 v176, v149, v149
	v_fmac_f32_e32 v176, v150, v150
	v_fmac_f32_e32 v176, v151, v151
	s_waitcnt lgkmcnt(2)
	v_add_f32_e32 v26, v194, v26
	v_add_f32_e32 v27, v195, v27
	v_add_f32_e32 v28, v196, v28
	v_add_f32_e32 v29, v197, v29
	v_add_f32_dpp v176, v176, v176 quad_perm:[1,0,3,2] row_mask:0xf bank_mask:0xf bound_ctrl:1
	v_mul_f32_e32 v26, 0xbfb8aa3b, v26
	v_mul_f32_e32 v27, 0xbfb8aa3b, v27
	v_mul_f32_e32 v28, 0xbfb8aa3b, v28
	v_mul_f32_e32 v29, 0xbfb8aa3b, v29
	v_add_f32_dpp v176, v176, v176 quad_perm:[2,3,0,1] row_mask:0xf bank_mask:0xf bound_ctrl:1
	v_exp_f32_e32 v26, v26
	v_exp_f32_e32 v27, v27
	v_exp_f32_e32 v28, v28
	v_exp_f32_e32 v29, v29
	v_add_f32_dpp v176, v176, v176 row_half_mirror row_mask:0xf bank_mask:0xf bound_ctrl:1
	v_add_f32_e32 v26, 1.0, v26
	v_add_f32_e32 v27, 1.0, v27
	v_add_f32_e32 v28, 1.0, v28
	v_add_f32_e32 v29, 1.0, v29
	v_add_f32_dpp v176, v176, v176 row_mirror row_mask:0xf bank_mask:0xf bound_ctrl:1
	v_rcp_f32_e32 v26, v26
	v_rcp_f32_e32 v27, v27
	v_rcp_f32_e32 v28, v28
	v_rcp_f32_e32 v29, v29
	v_sqrt_f32_e32 v176, v176
	v_add_f32_e32 v22, v190, v22
	v_add_f32_e32 v23, v191, v23
	v_add_f32_e32 v24, v192, v24
	v_add_f32_e32 v25, v193, v25
	v_max_f32_e32 v176, 0x2b8cbccc, v176
	v_mul_f32_e32 v22, 0xbfb8aa3b, v22
	v_mul_f32_e32 v23, 0xbfb8aa3b, v23
	v_mul_f32_e32 v24, 0xbfb8aa3b, v24
	v_mul_f32_e32 v25, 0xbfb8aa3b, v25
	v_rcp_f32_e32 v178, v176
	v_exp_f32_e32 v22, v22
	v_exp_f32_e32 v23, v23
	v_exp_f32_e32 v24, v24
	v_exp_f32_e32 v25, v25
	v_add_f32_e32 v22, 1.0, v22
	v_add_f32_e32 v23, 1.0, v23
	v_add_f32_e32 v24, 1.0, v24
	v_add_f32_e32 v25, 1.0, v25
	v_rcp_f32_e32 v22, v22
	v_rcp_f32_e32 v23, v23
	v_rcp_f32_e32 v24, v24
	v_rcp_f32_e32 v25, v25
	v_mul_f32_e32 v22, 0xbf1b4598, v22
	v_mul_f32_e32 v23, 0xbf1b4598, v23
	v_mul_f32_e32 v24, 0xbf1b4598, v24
	v_mul_f32_e32 v25, 0xbf1b4598, v25
	v_mul_f32_e32 v22, 0x3fb8aa3b, v22
	v_mul_f32_e32 v23, 0x3fb8aa3b, v23
	v_mul_f32_e32 v24, 0x3fb8aa3b, v24
	v_mul_f32_e32 v25, 0x3fb8aa3b, v25
	v_exp_f32_e32 v22, v22
	v_exp_f32_e32 v23, v23
	v_exp_f32_e32 v24, v24
	v_exp_f32_e32 v25, v25
	v_add_f32_e32 v152, -1.0, v26
	v_add_f32_e32 v153, -1.0, v27
	v_add_f32_e32 v154, -1.0, v28
	v_add_f32_e32 v155, -1.0, v29
	v_fma_f32 v152, v202, v152, 1.0
	v_fma_f32 v153, v203, v153, 1.0
	v_fma_f32 v154, v204, v154, 1.0
	v_fma_f32 v155, v205, v155, 1.0
	v_mul_f32_e32 v152, v136, v152
	v_mul_f32_e32 v153, v224, v153
	v_mul_f32_e32 v154, v137, v154
	v_mul_f32_e32 v155, v225, v155
	v_mul_f32_e32 v156, v134, v152
	v_mul_f32_e32 v157, v222, v153
	v_mul_f32_e32 v158, v135, v154
	v_mul_f32_e32 v159, v223, v155
	v_mul_f32_e32 v177, v206, v156
	v_fmac_f32_e32 v177, v207, v157
	v_fmac_f32_e32 v177, v208, v158
	v_fmac_f32_e32 v177, v209, v159
	v_mul_f32_e32 v148, v148, v178
	v_mul_f32_e32 v149, v149, v178
	v_add_f32_dpp v177, v177, v177 quad_perm:[1,0,3,2] row_mask:0xf bank_mask:0xf bound_ctrl:1
	v_mul_f32_e32 v150, v150, v178
	v_mul_f32_e32 v151, v151, v178
	v_add_f32_dpp v177, v177, v177 quad_perm:[2,3,0,1] row_mask:0xf bank_mask:0xf bound_ctrl:1
	v_mul_f32_e32 v26, v26, v148
	v_mul_f32_e32 v27, v27, v149
	v_add_f32_dpp v177, v177, v177 row_half_mirror row_mask:0xf bank_mask:0xf bound_ctrl:1
	v_mul_f32_e32 v28, v28, v150
	v_mul_f32_e32 v29, v29, v151
	v_add_f32_dpp v177, v177, v177 row_mirror row_mask:0xf bank_mask:0xf bound_ctrl:1
	s_lshl_b32 s0, s56, 9
	s_add_u32 s62, s34, s0
	s_addc_u32 s63, s35, 0
	v_fmac_f32_e32 v146, v138, v177
	v_fmac_f32_e32 v234, v226, v177
	v_fmac_f32_e32 v147, v139, v177
	v_fmac_f32_e32 v235, v227, v177
	v_cvt_pk_bf16_f32 v72, v134, v222
	v_cvt_pk_bf16_f32 v73, v135, v223
	global_store_dwordx2 v250, v[72:73], s[62:63]
	v_cvt_pk_bf16_f32 v74, v22, v23
	v_cvt_pk_bf16_f32 v75, v24, v25
	s_add_u32 s0, s62, 0x500000
	s_addc_u32 s1, s63, 0
	global_store_dwordx2 v250, v[74:75], s[0:1]
	v_cvt_pk_bf16_f32 v180, v152, v153
	v_cvt_pk_bf16_f32 v181, v154, v155
	s_add_u32 s0, s62, 0xa00000
	s_addc_u32 s1, s63, 0
	global_store_dwordx2 v250, v[180:181], s[0:1]
	v_cvt_pk_bf16_f32 v72, v138, v226
	v_cvt_pk_bf16_f32 v73, v139, v227
	s_add_u32 s0, s62, 0xf00000
	s_addc_u32 s1, s63, 0
	global_store_dwordx2 v250, v[72:73], s[0:1]
	v_cvt_pk_bf16_f32 v74, v148, v149
	v_cvt_pk_bf16_f32 v75, v150, v151
	s_add_u32 s0, s62, 0x1400000
	s_addc_u32 s1, s63, 0
	global_store_dwordx2 v250, v[74:75], s[0:1]
	v_cvt_pk_bf16_f32 v180, v26, v27
	v_cvt_pk_bf16_f32 v181, v28, v29
	s_add_u32 s0, s62, 0x1900000
	s_addc_u32 s1, s63, 0
	global_store_dwordx2 v250, v[180:181], s[0:1]
	v_cvt_pk_bf16_f32 v72, v146, v234
	v_cvt_pk_bf16_f32 v73, v147, v235
	s_lshl_b32 s0, s56, 9
	s_add_u32 s0, s42, s0
	s_addc_u32 s1, s43, 0
	global_store_dwordx2 v250, v[72:73], s[0:1]
	s_waitcnt vmcnt(14)
	v_lshlrev_b32_e32 v134, 16, v236
	v_and_b32_e32 v236, 0xffff0000, v236
	v_lshlrev_b32_e32 v135, 16, v237
	v_and_b32_e32 v237, 0xffff0000, v237
	v_lshlrev_b32_e32 v136, 16, v238
	v_and_b32_e32 v238, 0xffff0000, v238
	v_lshlrev_b32_e32 v137, 16, v239
	v_and_b32_e32 v239, 0xffff0000, v239
	v_lshlrev_b32_e32 v138, 16, v240
	v_and_b32_e32 v240, 0xffff0000, v240
	v_lshlrev_b32_e32 v139, 16, v241
	v_and_b32_e32 v241, 0xffff0000, v241
	v_lshlrev_b32_e32 v140, 16, v242
	v_and_b32_e32 v242, 0xffff0000, v242
	v_lshlrev_b32_e32 v141, 16, v243
	v_and_b32_e32 v243, 0xffff0000, v243
	v_lshlrev_b32_e32 v142, 16, v244
	v_and_b32_e32 v244, 0xffff0000, v244
	v_lshlrev_b32_e32 v143, 16, v245
	v_and_b32_e32 v245, 0xffff0000, v245
	v_lshlrev_b32_e32 v144, 16, v246
	v_and_b32_e32 v246, 0xffff0000, v246
	v_lshlrev_b32_e32 v145, 16, v247
	v_and_b32_e32 v247, 0xffff0000, v247
	v_lshlrev_b32_e32 v146, 16, v248
	v_and_b32_e32 v248, 0xffff0000, v248
	v_lshlrev_b32_e32 v147, 16, v249
	v_and_b32_e32 v249, 0xffff0000, v249
	v_fma_f32 v140, s60, v140, -v134
	v_fma_f32 v242, s60, v242, -v236
	v_fma_f32 v141, s60, v141, -v135
	v_fma_f32 v243, s60, v243, -v237
	v_fmac_f32_e32 v134, v210, v140
	v_fmac_f32_e32 v236, v211, v242
	v_fmac_f32_e32 v135, v212, v141
	v_fmac_f32_e32 v237, v213, v243
	v_fma_f32 v142, s60, v142, -v136
	v_fma_f32 v244, s60, v244, -v238
	v_fma_f32 v143, s60, v143, -v137
	v_fma_f32 v245, s60, v245, -v239
	v_fmac_f32_e32 v136, v214, v142
	v_fmac_f32_e32 v238, v215, v244
	v_fmac_f32_e32 v137, v216, v143
	v_fmac_f32_e32 v239, v217, v245
	v_fma_f32 v144, s60, v144, -v138
	v_fma_f32 v246, s60, v246, -v240
	v_fma_f32 v145, s60, v145, -v139
	v_fma_f32 v247, s60, v247, -v241
	v_fmac_f32_e32 v138, v218, v144
	v_fmac_f32_e32 v240, v219, v246
	v_fmac_f32_e32 v139, v220, v145
	v_fmac_f32_e32 v241, v221, v247
	v_mul_f32_e32 v148, v198, v136
	v_mul_f32_e32 v149, v199, v238
	v_mul_f32_e32 v150, v200, v137
	v_mul_f32_e32 v151, v201, v239
	v_mul_f32_e32 v176, v148, v148
	v_fmac_f32_e32 v176, v149, v149
	v_fmac_f32_e32 v176, v150, v150
	v_fmac_f32_e32 v176, v151, v151
	s_waitcnt lgkmcnt(0)
	v_add_f32_e32 v18, v194, v18
	v_add_f32_e32 v19, v195, v19
	v_add_f32_e32 v20, v196, v20
	v_add_f32_e32 v21, v197, v21
	v_add_f32_dpp v176, v176, v176 quad_perm:[1,0,3,2] row_mask:0xf bank_mask:0xf bound_ctrl:1
	v_mul_f32_e32 v18, 0xbfb8aa3b, v18
	v_mul_f32_e32 v19, 0xbfb8aa3b, v19
	v_mul_f32_e32 v20, 0xbfb8aa3b, v20
	v_mul_f32_e32 v21, 0xbfb8aa3b, v21
	v_add_f32_dpp v176, v176, v176 quad_perm:[2,3,0,1] row_mask:0xf bank_mask:0xf bound_ctrl:1
	v_exp_f32_e32 v18, v18
	v_exp_f32_e32 v19, v19
	v_exp_f32_e32 v20, v20
	v_exp_f32_e32 v21, v21
	v_add_f32_dpp v176, v176, v176 row_half_mirror row_mask:0xf bank_mask:0xf bound_ctrl:1
	v_add_f32_e32 v18, 1.0, v18
	v_add_f32_e32 v19, 1.0, v19
	v_add_f32_e32 v20, 1.0, v20
	v_add_f32_e32 v21, 1.0, v21
	v_add_f32_dpp v176, v176, v176 row_mirror row_mask:0xf bank_mask:0xf bound_ctrl:1
	v_rcp_f32_e32 v18, v18
	v_rcp_f32_e32 v19, v19
	v_rcp_f32_e32 v20, v20
	v_rcp_f32_e32 v21, v21
	v_sqrt_f32_e32 v176, v176
	v_add_f32_e32 v14, v190, v14
	v_add_f32_e32 v15, v191, v15
	v_add_f32_e32 v16, v192, v16
	v_add_f32_e32 v17, v193, v17
	v_max_f32_e32 v176, 0x2b8cbccc, v176
	v_mul_f32_e32 v14, 0xbfb8aa3b, v14
	v_mul_f32_e32 v15, 0xbfb8aa3b, v15
	v_mul_f32_e32 v16, 0xbfb8aa3b, v16
	v_mul_f32_e32 v17, 0xbfb8aa3b, v17
	v_rcp_f32_e32 v178, v176
	v_exp_f32_e32 v14, v14
	v_exp_f32_e32 v15, v15
	v_exp_f32_e32 v16, v16
	v_exp_f32_e32 v17, v17
	v_add_f32_e32 v14, 1.0, v14
	v_add_f32_e32 v15, 1.0, v15
	v_add_f32_e32 v16, 1.0, v16
	v_add_f32_e32 v17, 1.0, v17
	v_rcp_f32_e32 v14, v14
	v_rcp_f32_e32 v15, v15
	v_rcp_f32_e32 v16, v16
	v_rcp_f32_e32 v17, v17
	v_mul_f32_e32 v14, 0xbf1b4598, v14
	v_mul_f32_e32 v15, 0xbf1b4598, v15
	v_mul_f32_e32 v16, 0xbf1b4598, v16
	v_mul_f32_e32 v17, 0xbf1b4598, v17
	v_mul_f32_e32 v14, 0x3fb8aa3b, v14
	v_mul_f32_e32 v15, 0x3fb8aa3b, v15
	v_mul_f32_e32 v16, 0x3fb8aa3b, v16
	v_mul_f32_e32 v17, 0x3fb8aa3b, v17
	v_exp_f32_e32 v14, v14
	v_exp_f32_e32 v15, v15
	v_exp_f32_e32 v16, v16
	v_exp_f32_e32 v17, v17
	v_add_f32_e32 v152, -1.0, v18
	v_add_f32_e32 v153, -1.0, v19
	v_add_f32_e32 v154, -1.0, v20
	v_add_f32_e32 v155, -1.0, v21
	v_fma_f32 v152, v202, v152, 1.0
	v_fma_f32 v153, v203, v153, 1.0
	v_fma_f32 v154, v204, v154, 1.0
	v_fma_f32 v155, v205, v155, 1.0
	v_mul_f32_e32 v152, v136, v152
	v_mul_f32_e32 v153, v238, v153
	v_mul_f32_e32 v154, v137, v154
	v_mul_f32_e32 v155, v239, v155
	v_mul_f32_e32 v156, v134, v152
	v_mul_f32_e32 v157, v236, v153
	v_mul_f32_e32 v158, v135, v154
	v_mul_f32_e32 v159, v237, v155
	v_mul_f32_e32 v177, v206, v156
	v_fmac_f32_e32 v177, v207, v157
	v_fmac_f32_e32 v177, v208, v158
	v_fmac_f32_e32 v177, v209, v159
	v_mul_f32_e32 v148, v148, v178
	v_mul_f32_e32 v149, v149, v178
	v_add_f32_dpp v177, v177, v177 quad_perm:[1,0,3,2] row_mask:0xf bank_mask:0xf bound_ctrl:1
	v_mul_f32_e32 v150, v150, v178
	v_mul_f32_e32 v151, v151, v178
	v_add_f32_dpp v177, v177, v177 quad_perm:[2,3,0,1] row_mask:0xf bank_mask:0xf bound_ctrl:1
	v_mul_f32_e32 v18, v18, v148
	v_mul_f32_e32 v19, v19, v149
	v_add_f32_dpp v177, v177, v177 row_half_mirror row_mask:0xf bank_mask:0xf bound_ctrl:1
	v_mul_f32_e32 v20, v20, v150
	v_mul_f32_e32 v21, v21, v151
	v_add_f32_dpp v177, v177, v177 row_mirror row_mask:0xf bank_mask:0xf bound_ctrl:1
	s_lshl_b32 s0, s57, 9
	s_add_u32 s62, s34, s0
	s_addc_u32 s63, s35, 0
	v_fmac_f32_e32 v146, v138, v177
	v_fmac_f32_e32 v248, v240, v177
	v_fmac_f32_e32 v147, v139, v177
	v_fmac_f32_e32 v249, v241, v177
	v_cvt_pk_bf16_f32 v72, v134, v236
	v_cvt_pk_bf16_f32 v73, v135, v237
	global_store_dwordx2 v250, v[72:73], s[62:63]
	v_cvt_pk_bf16_f32 v74, v14, v15
	v_cvt_pk_bf16_f32 v75, v16, v17
	s_add_u32 s0, s62, 0x500000
	s_addc_u32 s1, s63, 0
	global_store_dwordx2 v250, v[74:75], s[0:1]
	v_cvt_pk_bf16_f32 v180, v152, v153
	v_cvt_pk_bf16_f32 v181, v154, v155
	s_add_u32 s0, s62, 0xa00000
	s_addc_u32 s1, s63, 0
	global_store_dwordx2 v250, v[180:181], s[0:1]
	v_cvt_pk_bf16_f32 v72, v138, v240
	v_cvt_pk_bf16_f32 v73, v139, v241
	s_add_u32 s0, s62, 0xf00000
	s_addc_u32 s1, s63, 0
	global_store_dwordx2 v250, v[72:73], s[0:1]
	v_cvt_pk_bf16_f32 v74, v148, v149
	v_cvt_pk_bf16_f32 v75, v150, v151
	s_add_u32 s0, s62, 0x1400000
	s_addc_u32 s1, s63, 0
	global_store_dwordx2 v250, v[74:75], s[0:1]
	v_cvt_pk_bf16_f32 v180, v18, v19
	v_cvt_pk_bf16_f32 v181, v20, v21
	s_add_u32 s0, s62, 0x1900000
	s_addc_u32 s1, s63, 0
	global_store_dwordx2 v250, v[180:181], s[0:1]
	v_cvt_pk_bf16_f32 v72, v146, v248
	v_cvt_pk_bf16_f32 v73, v147, v249
	s_lshl_b32 s0, s57, 9
	s_add_u32 s0, s42, s0
	s_addc_u32 s1, s43, 0
	global_store_dwordx2 v250, v[72:73], s[0:1]
	s_branch .LBB0_476
